# hg_out cross-chunk MFMAs: LDS reads 4 ahead; mixer item loops leave previous stores in flight at loop top
# speedup vs baseline: 1.0181x; 1.0005x over previous
.LBB0_271:
	s_cmpk_gt_i32 s8, 0x7ff
	s_cbranch_scc1 .LBB0_290
	s_lshl_b32 s9, s8, 23
	s_and_b32 s9, s9, 0x1800000
	s_add_u32 s9, s86, s9
	s_addc_u32 s14, s87, 0
	s_add_u32 s10, s9, 0xa000000
	v_add_u32_e32 v64, 0x200, v62
	s_addc_u32 s11, s14, 0
	s_ashr_i32 s12, s8, 2
	v_ashrrev_i32_e32 v63, 31, v62
	v_ashrrev_i32_e32 v65, 31, v64
	s_ashr_i32 s13, s12, 31
	v_lshlrev_b64 v[58:59], 3, v[62:63]
	v_lshlrev_b64 v[60:61], 3, v[64:65]
	s_lshl_b64 s[12:13], s[12:13], 13
	s_waitcnt vmcnt(0)
	v_lshl_add_u64 v[2:3], s[12:13], 0, v[58:59]
	v_lshl_add_u64 v[4:5], s[12:13], 0, v[60:61]
	v_lshlrev_b64 v[18:19], 1, v[2:3]
	v_lshlrev_b64 v[20:21], 1, v[4:5]
	v_lshl_add_u64 v[2:3], s[10:11], 0, v[18:19]
	v_lshl_add_u64 v[6:7], s[10:11], 0, v[20:21]
	s_add_u32 s10, s9, 0xc000000
	s_addc_u32 s11, s14, 0
	v_lshl_add_u64 v[10:11], s[10:11], 0, v[18:19]
	v_lshl_add_u64 v[14:15], s[10:11], 0, v[20:21]
	s_add_u32 s10, s9, 0xe000000
	s_addc_u32 s11, s14, 0
	v_lshl_add_u64 v[18:19], s[10:11], 0, v[18:19]
	v_lshl_add_u64 v[22:23], s[10:11], 0, v[20:21]
	global_load_dwordx4 v[2:5], v[2:3], off
	s_nop 0
	global_load_dwordx4 v[6:9], v[6:7], off
	s_nop 0
	global_load_dwordx4 v[10:13], v[10:11], off
	s_nop 0
	global_load_dwordx4 v[14:17], v[14:15], off
	s_nop 0
	global_load_dwordx4 v[18:21], v[18:19], off
	s_nop 0
	global_load_dwordx4 v[22:25], v[22:23], off
	v_lshlrev_b32_e32 v63, 3, v62
	v_and_b32_e32 v0, 0x78, v63
	v_ashrrev_i32_e32 v26, 4, v62
	s_movk_i32 s9, 0x88
	v_mad_u64_u32 v[28:29], s[10:11], v26, s9, v[0:1]
	v_lshl_add_u32 v90, v28, 1, 0
	v_ashrrev_i32_e32 v28, 4, v64
	v_mad_u64_u32 v[30:31], s[10:11], v28, s9, v[0:1]
	s_add_i32 s9, 0, 0x4400
	s_movk_i32 s10, 0x100
	v_and_b32_e32 v27, 63, v62
	v_mov_b32_e32 v29, s9
	v_cmp_gt_u32_e32 vcc, s10, v62
	v_lshlrev_b32_e32 v32, 2, v27
	v_lshl_add_u32 v92, v30, 1, 0
	v_cndmask_b32_e64 v29, v29, 0, vcc
	v_add_u32_e32 v93, v29, v32
	v_ashrrev_i32_e32 v29, 6, v62
	v_and_b32_e32 v108, -4, v29
	v_lshl_or_b32 v34, v29, 9, v180
	v_ashrrev_i32_e32 v30, 7, v62
	v_lshlrev_b32_e32 v29, 2, v62
	v_lshl_add_u32 v109, v27, 3, 0
	v_lshlrev_b32_e32 v27, 11, v30
	v_and_b32_e32 v35, 0x1fc, v29
	v_add3_u32 v110, 0, v27, v35
	s_ashr_i32 s24, s3, 8
	s_bfe_u32 s3, s3, 0x20006
	v_bfe_u32 v27, v62, 4, 2
	s_cmp_lt_u32 s17, 4
	v_bfe_u32 v29, v62, 2, 2
	v_lshlrev_b32_e32 v91, 2, v27
	v_cmp_gt_i32_e64 s[40:41], s10, v62
	s_cselect_b32 s9, 0, s9
	v_lshl_or_b32 v88, v27, 3, v29
	s_lshl_b32 s10, s3, 6
	v_lshl_or_b32 v27, s3, 5, v91
	s_lshl_b32 s3, s24, 11
	s_add_i32 s3, s3, 0
	v_lshlrev_b32_e32 v0, 1, v0
	v_and_b32_e32 v65, 15, v62
	v_and_b32_e32 v29, 12, v32
	v_lshl_add_u32 v111, v27, 2, s3
	v_lshl_add_u32 v112, v27, 1, 0
	v_add_u32_e32 v44, 0, v0
	v_lshl_add_u64 v[66:67], s[46:47], 0, v[0:1]
	v_ashrrev_i32_e32 v27, 31, v26
	v_add_u32_e32 v0, 0x400, v62
	v_lshlrev_b32_e32 v89, 1, v29
	v_lshl_or_b32 v29, s24, 7, v65
	v_mul_lo_u32 v45, v26, s18
	v_lshlrev_b64 v[68:69], 8, v[26:27]
	v_ashrrev_i32_e32 v26, 4, v0
	v_mul_lo_u32 v113, v29, s18
	v_ashrrev_i32_e32 v29, 31, v28
	v_ashrrev_i32_e32 v27, 31, v26
	v_add_u32_e32 v0, 0x600, v62
	v_mul_lo_u32 v46, v28, s18
	v_lshlrev_b64 v[70:71], 8, v[28:29]
	v_mul_lo_u32 v28, v26, s18
	v_lshlrev_b64 v[72:73], 8, v[26:27]
	v_ashrrev_i32_e32 v26, 4, v0
	v_ashrrev_i32_e32 v27, 31, v26
	v_add_u32_e32 v0, 0x800, v62
	v_mul_lo_u32 v29, v26, s18
	v_lshlrev_b64 v[74:75], 8, v[26:27]
	v_ashrrev_i32_e32 v26, 4, v0
	v_ashrrev_i32_e32 v27, 31, v26
	v_add_u32_e32 v0, 0xa00, v62
	v_mul_lo_u32 v47, v26, s18
	v_lshlrev_b64 v[76:77], 8, v[26:27]
	v_ashrrev_i32_e32 v26, 4, v0
	v_ashrrev_i32_e32 v27, 31, v26
	v_add_u32_e32 v0, 0xc00, v62
	v_mul_lo_u32 v48, v26, s18
	v_lshlrev_b64 v[78:79], 8, v[26:27]
	v_ashrrev_i32_e32 v26, 4, v0
	s_add_i32 s9, s9, s10
	v_ashrrev_i32_e32 v27, 31, v26
	v_add_u32_e32 v0, 0xe00, v62
	v_ashrrev_i32_e32 v31, 31, v30
	v_add_u32_e32 v32, s9, v89
	v_mul_lo_u32 v49, v26, s18
	v_lshlrev_b64 v[80:81], 8, v[26:27]
	v_ashrrev_i32_e32 v26, 4, v0
	s_ashr_i32 s9, s8, 31
	v_lshlrev_b64 v[30:31], 9, v[30:31]
	v_ashrrev_i32_e32 v27, 31, v26
	s_lshl_b64 s[10:11], s[8:9], 10
	v_mul_lo_u32 v50, v26, s18
	v_lshlrev_b64 v[82:83], 8, v[26:27]
	v_lshl_add_u64 v[26:27], s[10:11], 0, v[30:31]
	v_lshlrev_b32_e32 v33, 9, v108
	v_add_u32_e32 v36, 0, v89
	v_mul_u32_u24_e32 v37, 0x110, v88
	v_add_u32_e32 v38, 0x2200, v113
	v_add_u32_e32 v39, 0x3300, v113
	v_add_u32_e32 v40, 0x4400, v113
	v_add_u32_e32 v41, 0x5500, v113
	v_add_u32_e32 v42, 0x6600, v113
	v_add_u32_e32 v43, 0x7700, v113
	s_ashr_i32 s3, s2, 31
	v_or_b32_e32 v26, v26, v35
	v_cndmask_b32_e64 v94, 14, 1, vcc
	v_cndmask_b32_e64 v95, 13, 2, vcc
	v_cndmask_b32_e64 v96, 12, 3, vcc
	v_cndmask_b32_e64 v97, 11, 4, vcc
	v_cndmask_b32_e64 v98, 10, 5, vcc
	v_cndmask_b32_e64 v99, 9, 6, vcc
	v_cndmask_b32_e64 v100, 8, 7, vcc
	v_cndmask_b32_e64 v101, 7, 8, vcc
	v_cndmask_b32_e64 v102, 6, 9, vcc
	v_cndmask_b32_e64 v103, 5, 10, vcc
	v_cndmask_b32_e64 v104, 4, 11, vcc
	v_cndmask_b32_e64 v105, 3, 12, vcc
	v_cndmask_b32_e64 v106, 2, 13, vcc
	v_cndmask_b32_e64 v107, 1, 14, vcc
	v_lshl_add_u64 v[84:85], s[94:95], 0, v[26:27]
	s_lshl_b64 s[10:11], s[2:3], 10
	v_add_u32_e32 v0, v109, v34
	v_add_u32_e32 v114, v32, v37
	v_add_u32_e32 v115, v36, v37
	v_add_u32_e32 v116, v112, v38
	v_add_u32_e32 v117, v112, v39
	v_add_u32_e32 v118, v112, v40
	v_add_u32_e32 v119, v112, v41
	v_add_u32_e32 v120, v112, v42
	v_add_u32_e32 v121, v112, v43
	v_add_u32_e32 v122, v44, v45
	v_add_u32_e32 v123, v44, v46
	v_add_u32_e32 v124, v44, v28
	v_add_u32_e32 v125, v44, v29
	v_add_u32_e32 v126, v44, v47
	v_add_u32_e32 v127, v44, v48
	v_add_u32_e32 v128, v44, v49
	v_add_u32_e32 v129, v44, v50
	v_add_u32_e32 v130, v109, v33
	s_mov_b64 s[12:13], s[8:9]
	s_waitcnt vmcnt(0)
	s_branch .LBB0_274

.LBB0_274:
	s_add_i32 s14, s2, s12
	s_cmpk_lt_i32 s14, 0x800
	s_cselect_b32 s14, s14, -1
	s_cmp_lt_i32 s14, 0
	s_waitcnt vmcnt(8)
	ds_write_b128 v90, v[2:5]
	ds_write_b128 v90, v[10:13] offset:17408
	ds_write_b128 v90, v[18:21] offset:34816
	ds_write_b128 v92, v[6:9]
	ds_write_b128 v92, v[14:17] offset:17408
	ds_write_b128 v92, v[22:25] offset:34816
	s_waitcnt lgkmcnt(0)
	s_barrier
	s_cbranch_scc1 .LBB0_276
	s_lshr_b32 s80, s14, 2
	s_lshl_b32 s14, s14, 23
	s_lshl_b64 s[26:27], s[80:81], 13
	s_and_b32 s14, s14, 0x1800000
	s_add_u32 s25, s86, s14
	s_addc_u32 s30, s87, 0
	s_add_u32 s14, s25, 0xa000000
	s_addc_u32 s15, s30, 0
	s_add_u32 s28, s25, 0xc000000
	v_lshl_add_u64 v[2:3], s[26:27], 0, v[58:59]
	s_addc_u32 s29, s30, 0
	v_lshlrev_b64 v[6:7], 1, v[2:3]
	v_lshl_add_u64 v[2:3], s[14:15], 0, v[6:7]
	v_lshl_add_u64 v[8:9], s[28:29], 0, v[6:7]
	s_add_u32 s42, s25, 0xe000000
	global_load_dwordx4 v[2:5], v[2:3], off
	s_nop 0
	global_load_dwordx4 v[10:13], v[8:9], off
	v_lshl_add_u64 v[8:9], s[26:27], 0, v[60:61]
	s_addc_u32 s43, s30, 0
	v_lshlrev_b64 v[14:15], 1, v[8:9]
	v_lshl_add_u64 v[6:7], s[42:43], 0, v[6:7]
	v_lshl_add_u64 v[8:9], s[14:15], 0, v[14:15]
	v_lshl_add_u64 v[16:17], s[28:29], 0, v[14:15]
	v_lshl_add_u64 v[22:23], s[42:43], 0, v[14:15]
	global_load_dwordx4 v[18:21], v[6:7], off
	s_nop 0
	global_load_dwordx4 v[6:9], v[8:9], off
	s_nop 0
	global_load_dwordx4 v[14:17], v[16:17], off
	s_nop 0
	global_load_dwordx4 v[22:25], v[22:23], off

.LBB0_286:
	s_lshl_b32 s10, s8, 22
	s_and_b32 s10, s10, 0x1c00000
	s_add_u32 s14, s86, s10
	s_addc_u32 s15, s87, 0
	s_add_u32 s10, s14, 0x4000000
	s_addc_u32 s11, s15, 0
	s_ashr_i32 s12, s8, 3
	s_ashr_i32 s13, s12, 31
	s_lshl_b64 s[12:13], s[12:13], 13
	s_waitcnt vmcnt(13)
	v_lshl_add_u64 v[2:3], s[12:13], 0, v[60:61]
	s_add_u32 s14, s14, 0x2000000
	v_lshlrev_b64 v[2:3], 1, v[2:3]
	s_addc_u32 s15, s15, 0
	v_lshl_add_u64 v[4:5], s[10:11], 0, v[2:3]
	v_lshl_add_u64 v[2:3], s[14:15], 0, v[2:3]
	global_load_dwordx4 v[14:17], v[4:5], off
	global_load_dwordx4 v[6:9], v[2:3], off
	v_lshl_add_u64 v[2:3], s[12:13], 0, v[58:59]
	v_lshlrev_b64 v[2:3], 1, v[2:3]
	v_lshl_add_u64 v[4:5], s[10:11], 0, v[2:3]
	v_lshl_add_u64 v[2:3], s[14:15], 0, v[2:3]
	global_load_dwordx4 v[10:13], v[4:5], off
	s_nop 0
	global_load_dwordx4 v[2:5], v[2:3], off
	v_and_b32_e32 v0, 56, v63
	v_lshl_add_u32 v0, v0, 1, 0
	s_waitcnt vmcnt(15)
	v_ashrrev_i32_e32 v18, 3, v62
	s_movk_i32 s12, 0x90
	v_sub_u32_e32 v19, 0x7f, v18
	v_cvt_f32_i32_e32 v43, v18
	v_mad_u64_u32 v[34:35], s[10:11], v18, s12, v[0:1]
	v_ashrrev_i32_e32 v18, 3, v64
	v_mad_u64_u32 v[36:37], s[10:11], v18, s12, v[0:1]
	s_lshl_b32 s10, s17, 4
	s_and_b32 s10, s10, 48
	s_lshl_b32 s11, s10, 1
	s_lshl_b32 s12, s24, 6
	v_mul_u32_u24_e32 v0, 0x48, v88
	v_cvt_f32_i32_e32 v42, v19
	v_sub_u32_e32 v19, 0x7f, v18
	v_cvt_f32_i32_e32 v44, v18
	s_add_i32 s11, s11, 0
	s_add_i32 s12, s12, 0
	v_lshlrev_b32_e32 v0, 1, v0
	v_lshl_or_b32 v18, s24, 5, v65
	v_cvt_f32_i32_e32 v35, v19
	v_add3_u32 v37, s11, v89, v0
	v_add3_u32 v45, s12, v89, v0
	v_or_b32_e32 v0, s10, v91
	s_lshl_b64 s[10:11], s[8:9], 14
	v_or_b32_e32 v20, 16, v18
	v_ashrrev_i32_e32 v21, 31, v20
	s_add_u32 s12, s76, s10
	v_ashrrev_i32_e32 v19, 31, v18
	v_lshlrev_b64 v[20:21], 7, v[20:21]
	s_addc_u32 s13, s77, s11
	v_lshlrev_b64 v[18:19], 7, v[18:19]
	v_lshlrev_b32_e32 v0, 1, v0
	v_lshl_add_u64 v[38:39], s[12:13], 0, v[20:21]
	s_lshl_b64 s[10:11], s[2:3], 14
	v_lshl_add_u64 v[40:41], s[12:13], 0, v[18:19]
	s_waitcnt vmcnt(0)
	s_branch .LBB0_288

.LBB0_288:
	s_mov_b32 s9, s8
	s_add_i32 s8, s8, s2
	s_cmpk_gt_i32 s8, 0x7ff
	s_cselect_b64 s[12:13], -1, 0
	s_cmpk_lt_i32 s8, 0x800
	s_cselect_b32 s3, s8, -1
	s_and_b32 s9, s9, 7
	s_cmp_eq_u32 s9, 1
	s_cselect_b64 vcc, -1, 0
	s_cmp_lg_u32 s9, 2
	v_cndmask_b32_e32 v18, v181, v182, vcc
	s_cselect_b64 vcc, -1, 0
	s_cmp_lg_u32 s9, 3
	v_cndmask_b32_e32 v18, v183, v18, vcc
	s_cselect_b64 vcc, -1, 0
	s_cmp_lg_u32 s9, 4
	v_cndmask_b32_e32 v18, v184, v18, vcc
	s_cselect_b64 vcc, -1, 0
	s_cmp_lg_u32 s9, 5
	v_cndmask_b32_e32 v18, v185, v18, vcc
	s_cselect_b64 vcc, -1, 0
	s_cmp_lg_u32 s9, 6
	v_cndmask_b32_e32 v18, v186, v18, vcc
	s_cselect_b64 vcc, -1, 0
	s_cmp_lg_u32 s9, 7
	v_cndmask_b32_e32 v18, v187, v18, vcc
	s_cselect_b64 vcc, -1, 0
	v_cndmask_b32_e32 v31, v188, v18, vcc
	v_mul_f32_e32 v18, v31, v42
	v_exp_f32_e32 v18, v18
	v_mul_f32_e32 v19, v31, v43
	v_exp_f32_e32 v30, v19
	s_waitcnt vmcnt(4)
	v_lshlrev_b32_e32 v22, 16, v2
	v_and_b32_e32 v23, 0xffff0000, v2
	v_lshlrev_b32_e32 v24, 16, v3
	v_and_b32_e32 v25, 0xffff0000, v3
	v_lshlrev_b32_e32 v26, 16, v4
	v_and_b32_e32 v27, 0xffff0000, v4
	v_lshlrev_b32_e32 v28, 16, v5
	v_and_b32_e32 v29, 0xffff0000, v5
	v_pk_mul_f32 v[20:21], v[18:19], v[24:25] op_sel_hi:[0,1]
	v_pk_mul_f32 v[32:33], v[18:19], v[22:23] op_sel_hi:[0,1]
	v_pk_mul_f32 v[46:47], v[18:19], v[28:29] op_sel_hi:[0,1]
	v_pk_mul_f32 v[48:49], v[18:19], v[26:27] op_sel_hi:[0,1]
	v_cvt_pk_bf16_f32 v18, v32, v33
	v_cvt_pk_bf16_f32 v19, v20, v21
	v_cvt_pk_bf16_f32 v20, v48, v49
	v_cvt_pk_bf16_f32 v21, v46, v47
	ds_write_b128 v34, v[18:21]
	v_pk_mul_f32 v[20:21], v[30:31], v[24:25] op_sel_hi:[0,1]
	v_pk_mul_f32 v[18:19], v[30:31], v[22:23] op_sel_hi:[0,1]
	v_pk_mul_f32 v[22:23], v[30:31], v[28:29] op_sel_hi:[0,1]
	v_pk_mul_f32 v[24:25], v[30:31], v[26:27] op_sel_hi:[0,1]
	v_cvt_pk_bf16_f32 v18, v18, v19
	v_cvt_pk_bf16_f32 v19, v20, v21
	v_cvt_pk_bf16_f32 v20, v24, v25
	v_cvt_pk_bf16_f32 v21, v22, v23
	ds_write_b128 v34, v[18:21] offset:18432
	ds_write_b128 v34, v[10:13] offset:36864
	v_mul_f32_e32 v18, v31, v35
	v_exp_f32_e32 v18, v18
	v_mul_f32_e32 v19, v31, v44
	v_exp_f32_e32 v30, v19
	v_lshlrev_b32_e32 v22, 16, v6
	v_and_b32_e32 v23, 0xffff0000, v6
	v_lshlrev_b32_e32 v24, 16, v7
	v_and_b32_e32 v25, 0xffff0000, v7
	v_lshlrev_b32_e32 v26, 16, v8
	v_and_b32_e32 v27, 0xffff0000, v8
	v_lshlrev_b32_e32 v28, 16, v9
	v_and_b32_e32 v29, 0xffff0000, v9
	v_pk_mul_f32 v[20:21], v[18:19], v[24:25] op_sel_hi:[0,1]
	v_pk_mul_f32 v[32:33], v[18:19], v[22:23] op_sel_hi:[0,1]
	v_pk_mul_f32 v[46:47], v[18:19], v[28:29] op_sel_hi:[0,1]
	v_pk_mul_f32 v[48:49], v[18:19], v[26:27] op_sel_hi:[0,1]
	v_cvt_pk_bf16_f32 v18, v32, v33
	v_cvt_pk_bf16_f32 v19, v20, v21
	v_cvt_pk_bf16_f32 v20, v48, v49
	v_cvt_pk_bf16_f32 v21, v46, v47
	ds_write_b128 v36, v[18:21]
	v_pk_mul_f32 v[20:21], v[30:31], v[24:25] op_sel_hi:[0,1]
	v_pk_mul_f32 v[18:19], v[30:31], v[22:23] op_sel_hi:[0,1]
	v_pk_mul_f32 v[22:23], v[30:31], v[28:29] op_sel_hi:[0,1]
	v_pk_mul_f32 v[24:25], v[30:31], v[26:27] op_sel_hi:[0,1]
	v_cvt_pk_bf16_f32 v18, v18, v19
	v_cvt_pk_bf16_f32 v19, v20, v21
	v_cvt_pk_bf16_f32 v20, v24, v25
	v_cvt_pk_bf16_f32 v21, v22, v23
	s_cmp_lt_i32 s3, 0
	ds_write_b128 v36, v[18:21] offset:18432
	ds_write_b128 v36, v[14:17] offset:36864
	s_waitcnt lgkmcnt(0)
	s_barrier
	s_cbranch_scc1 .LBB0_287
	s_lshr_b32 s80, s3, 3
	s_lshl_b32 s3, s3, 22
	s_lshl_b64 s[14:15], s[80:81], 13
	s_and_b32 s3, s3, 0x1c00000
	s_add_u32 s3, s86, s3
	s_addc_u32 s9, s87, 0
	s_add_u32 s24, s3, 0x2000000
	s_addc_u32 s25, s9, 0
	s_add_u32 s26, s3, 0x4000000
	v_lshl_add_u64 v[2:3], s[14:15], 0, v[58:59]
	s_addc_u32 s27, s9, 0
	v_lshlrev_b64 v[2:3], 1, v[2:3]
	v_lshl_add_u64 v[4:5], s[24:25], 0, v[2:3]
	v_lshl_add_u64 v[6:7], s[26:27], 0, v[2:3]
	global_load_dwordx4 v[2:5], v[4:5], off
	s_nop 0
	global_load_dwordx4 v[10:13], v[6:7], off
	v_lshl_add_u64 v[6:7], s[14:15], 0, v[60:61]
	v_lshlrev_b64 v[6:7], 1, v[6:7]
	v_lshl_add_u64 v[8:9], s[24:25], 0, v[6:7]
	v_lshl_add_u64 v[14:15], s[26:27], 0, v[6:7]
	global_load_dwordx4 v[6:9], v[8:9], off
	s_nop 0
	global_load_dwordx4 v[14:17], v[14:15], off
	s_branch .LBB0_287

.LBB0_444:
	s_or_b64 exec, exec, s[14:15]
	v_mul_u32_u24_e32 v147, 0x44, v173
	v_lshl_add_u32 v147, v147, 2, v113
	ds_read_b32 v175, v147
	v_mad_u32_u24 v173, v173, s20, v102
	v_lshl_add_u32 v173, v173, 2, v135
	ds_read_b32 v177, v173
	s_ashr_i32 s14, s29, 2
	s_waitcnt lgkmcnt(1)
	v_lshlrev_b32_e32 v174, 16, v175
	v_and_b32_e32 v175, 0xffff0000, v175
	v_pk_add_f32 v[198:199], v[174:175], 1.0 op_sel_hi:[1,0] neg_lo:[1,0] neg_hi:[1,0]
	s_waitcnt lgkmcnt(0)
	v_lshlrev_b32_e32 v176, 16, v177
	v_pk_mul_f32 v[84:85], v[84:85], v[198:199]
	v_and_b32_e32 v177, 0xffff0000, v177
	v_max_f32_e32 v197, 0xda24260, v84
	v_rcp_f32_e32 v198, v197
	v_max_f32_e32 v197, 0xda24260, v85
	v_rcp_f32_e32 v199, v197
	s_ashr_i32 s15, s14, 31
	s_lshl_b64 vcc, s[14:15], 6
	s_and_b32 s14, s29, 3
	v_pk_mul_f32 v[174:175], v[198:199], v[174:175]
	s_lshl_b32 s15, s14, 23
	v_cvt_pk_bf16_f32 v174, v174, v175
	ds_write_b32 v147, v174
	v_pk_mul_f32 v[174:175], v[84:85], v[176:177]
	s_add_u32 s16, s86, s15
	v_cvt_pk_bf16_f32 v147, v174, v175
	ds_write_b32 v173, v147
	global_load_dwordx4 v[50:53], v[34:35], off
	v_mul_u32_u24_e32 v147, 0x44, v172
	v_lshl_add_u32 v147, v147, 2, v113
	ds_read_b32 v173, v147
	v_mad_u32_u24 v174, v172, s20, v102
	v_lshl_add_u32 v197, v174, 2, v135
	ds_read_b32 v175, v197
	s_addc_u32 s17, s87, 0
	s_waitcnt lgkmcnt(1)
	v_lshlrev_b32_e32 v172, 16, v173
	v_and_b32_e32 v173, 0xffff0000, v173
	v_pk_add_f32 v[176:177], v[172:173], 1.0 op_sel_hi:[1,0] neg_lo:[1,0] neg_hi:[1,0]
	s_waitcnt lgkmcnt(0)
	v_lshlrev_b32_e32 v174, 16, v175
	v_pk_mul_f32 v[84:85], v[84:85], v[176:177]
	v_and_b32_e32 v175, 0xffff0000, v175
	v_max_f32_e32 v176, 0xda24260, v84
	v_max_f32_e32 v177, 0xda24260, v85
	v_rcp_f32_e32 v176, v176
	v_rcp_f32_e32 v177, v177
	s_brev_b32 s15, 8
	s_lshl_b32 s80, s14, 9
	v_pk_mul_f32 v[172:173], v[176:177], v[172:173]
	s_mov_b32 s29, s28
	v_cvt_pk_bf16_f32 v172, v172, v173
	ds_write_b32 v147, v172
	v_pk_mul_f32 v[172:173], v[84:85], v[174:175]
	s_nop 0
	v_cvt_pk_bf16_f32 v147, v172, v173
	ds_write_b32 v197, v147
	global_load_dwordx4 v[46:49], v[82:83], off offset:-192
	v_mul_u32_u24_e32 v147, 0x44, v171
	v_lshl_add_u32 v147, v147, 2, v113
	ds_read_b32 v173, v147
	v_mad_u32_u24 v171, v171, s20, v102
	v_lshl_add_u32 v171, v171, 2, v135
	ds_read_b32 v175, v171
	s_waitcnt lgkmcnt(1)
	v_lshlrev_b32_e32 v172, 16, v173
	v_and_b32_e32 v173, 0xffff0000, v173
	v_pk_add_f32 v[176:177], v[172:173], 1.0 op_sel_hi:[1,0] neg_lo:[1,0] neg_hi:[1,0]
	s_waitcnt lgkmcnt(0)
	v_lshlrev_b32_e32 v174, 16, v175
	v_pk_mul_f32 v[84:85], v[84:85], v[176:177]
	v_and_b32_e32 v175, 0xffff0000, v175
	v_max_f32_e32 v176, 0xda24260, v84
	v_max_f32_e32 v177, 0xda24260, v85
	v_rcp_f32_e32 v176, v176
	v_rcp_f32_e32 v177, v177
	s_nop 0
	v_pk_mul_f32 v[172:173], v[176:177], v[172:173]
	s_nop 0
	v_cvt_pk_bf16_f32 v172, v172, v173
	ds_write_b32 v147, v172
	v_pk_mul_f32 v[172:173], v[84:85], v[174:175]
	s_nop 0
	v_cvt_pk_bf16_f32 v147, v172, v173
	ds_write_b32 v171, v147
	global_load_dwordx4 v[42:45], v[82:83], off offset:-128
	v_mul_u32_u24_e32 v147, 0x44, v170
	v_lshl_add_u32 v147, v147, 2, v113
	ds_read_b32 v171, v147
	v_mad_u32_u24 v172, v170, s20, v102
	v_lshl_add_u32 v176, v172, 2, v135
	ds_read_b32 v173, v176
	s_waitcnt lgkmcnt(1)
	v_lshlrev_b32_e32 v170, 16, v171
	v_and_b32_e32 v171, 0xffff0000, v171
	v_pk_add_f32 v[174:175], v[170:171], 1.0 op_sel_hi:[1,0] neg_lo:[1,0] neg_hi:[1,0]
	s_waitcnt lgkmcnt(0)
	v_lshlrev_b32_e32 v172, 16, v173
	v_pk_mul_f32 v[84:85], v[84:85], v[174:175]
	v_and_b32_e32 v173, 0xffff0000, v173
	v_max_f32_e32 v174, 0xda24260, v84
	v_max_f32_e32 v175, 0xda24260, v85
	v_rcp_f32_e32 v174, v174
	v_rcp_f32_e32 v175, v175
	s_nop 0
	v_pk_mul_f32 v[170:171], v[174:175], v[170:171]
	s_nop 0
	v_cvt_pk_bf16_f32 v170, v170, v171
	ds_write_b32 v147, v170
	v_pk_mul_f32 v[170:171], v[84:85], v[172:173]
	s_nop 0
	v_cvt_pk_bf16_f32 v147, v170, v171
	ds_write_b32 v176, v147
	global_load_dwordx4 v[38:41], v[82:83], off offset:-64
	v_mul_u32_u24_e32 v147, 0x44, v169
	v_lshl_add_u32 v147, v147, 2, v113
	ds_read_b32 v171, v147
	v_mad_u32_u24 v169, v169, s20, v102
	v_lshl_add_u32 v169, v169, 2, v135
	ds_read_b32 v173, v169
	v_add_u32_e32 v176, v137, v73
	s_waitcnt lgkmcnt(1)
	v_lshlrev_b32_e32 v170, 16, v171
	v_and_b32_e32 v171, 0xffff0000, v171
	v_pk_add_f32 v[174:175], v[170:171], 1.0 op_sel_hi:[1,0] neg_lo:[1,0] neg_hi:[1,0]
	s_waitcnt lgkmcnt(0)
	v_lshlrev_b32_e32 v172, 16, v173
	v_pk_mul_f32 v[84:85], v[84:85], v[174:175]
	v_and_b32_e32 v173, 0xffff0000, v173
	v_max_f32_e32 v174, 0xda24260, v84
	v_max_f32_e32 v175, 0xda24260, v85
	v_rcp_f32_e32 v174, v174
	v_rcp_f32_e32 v175, v175
	s_nop 0
	v_pk_mul_f32 v[170:171], v[174:175], v[170:171]
	s_nop 0
	v_cvt_pk_bf16_f32 v170, v170, v171
	ds_write_b32 v147, v170
	v_pk_mul_f32 v[170:171], v[84:85], v[172:173]
	s_nop 0
	v_cvt_pk_bf16_f32 v147, v170, v171
	ds_write_b32 v169, v147
	global_load_dwordx4 v[34:37], v[82:83], off
	v_lshl_add_u64 v[82:83], v[82:83], 0, s[10:11]
	v_mul_u32_u24_e32 v147, 0x44, v168
	v_lshl_add_u32 v147, v147, 2, v113
	ds_read_b32 v169, v147
	v_mad_u32_u24 v170, v168, s20, v102
	v_lshl_add_u32 v174, v170, 2, v135
	ds_read_b32 v171, v174
	s_waitcnt lgkmcnt(1)
	v_lshlrev_b32_e32 v168, 16, v169
	v_and_b32_e32 v169, 0xffff0000, v169
	v_pk_add_f32 v[172:173], v[168:169], 1.0 op_sel_hi:[1,0] neg_lo:[1,0] neg_hi:[1,0]
	s_waitcnt lgkmcnt(0)
	v_lshlrev_b32_e32 v170, 16, v171
	v_pk_mul_f32 v[84:85], v[84:85], v[172:173]
	v_and_b32_e32 v171, 0xffff0000, v171
	v_max_f32_e32 v172, 0xda24260, v84
	v_max_f32_e32 v173, 0xda24260, v85
	v_rcp_f32_e32 v172, v172
	v_rcp_f32_e32 v173, v173
	s_nop 0
	v_pk_mul_f32 v[168:169], v[172:173], v[168:169]
	s_nop 0
	v_cvt_pk_bf16_f32 v168, v168, v169
	ds_write_b32 v147, v168
	v_pk_mul_f32 v[168:169], v[84:85], v[170:171]
	s_nop 0
	v_cvt_pk_bf16_f32 v147, v168, v169
	ds_write_b32 v174, v147
	global_load_dwordx4 v[2:5], v236, s[100:101]
	v_mul_u32_u24_e32 v147, 0x44, v95
	v_lshl_add_u32 v147, v147, 2, v113
	ds_read_b32 v169, v147
	v_mad_u32_u24 v95, v95, s20, v102
	v_lshl_add_u32 v95, v95, 2, v135
	ds_read_b32 v171, v95
	s_waitcnt lgkmcnt(1)
	v_lshlrev_b32_e32 v168, 16, v169
	v_and_b32_e32 v169, 0xffff0000, v169
	v_pk_add_f32 v[172:173], v[168:169], 1.0 op_sel_hi:[1,0] neg_lo:[1,0] neg_hi:[1,0]
	s_waitcnt lgkmcnt(0)
	v_lshlrev_b32_e32 v170, 16, v171
	v_pk_mul_f32 v[84:85], v[84:85], v[172:173]
	v_and_b32_e32 v171, 0xffff0000, v171
	v_max_f32_e32 v172, 0xda24260, v84
	v_max_f32_e32 v173, 0xda24260, v85
	v_rcp_f32_e32 v172, v172
	v_rcp_f32_e32 v173, v173
	s_nop 0
	v_pk_mul_f32 v[168:169], v[172:173], v[168:169]
	s_nop 0
	v_cvt_pk_bf16_f32 v168, v168, v169
	ds_write_b32 v147, v168
	v_pk_mul_f32 v[168:169], v[84:85], v[170:171]
	s_nop 0
	v_cvt_pk_bf16_f32 v147, v168, v169
	ds_write_b32 v95, v147
	v_mul_u32_u24_e32 v95, 0x44, v94
	v_lshl_add_u32 v172, v95, 2, v113
	ds_read_b32 v95, v172
	v_mad_u32_u24 v147, v94, s20, v102
	v_lshl_add_u32 v147, v147, 2, v135
	ds_read_b32 v169, v147
	s_waitcnt lgkmcnt(1)
	v_lshlrev_b32_e32 v94, 16, v95
	v_and_b32_e32 v95, 0xffff0000, v95
	v_pk_add_f32 v[170:171], v[94:95], 1.0 op_sel_hi:[1,0] neg_lo:[1,0] neg_hi:[1,0]
	s_waitcnt lgkmcnt(0)
	v_lshlrev_b32_e32 v168, 16, v169
	v_pk_mul_f32 v[84:85], v[84:85], v[170:171]
	v_and_b32_e32 v169, 0xffff0000, v169
	v_max_f32_e32 v170, 0xda24260, v84
	v_max_f32_e32 v171, 0xda24260, v85
	v_rcp_f32_e32 v170, v170
	v_rcp_f32_e32 v171, v171
	s_nop 0
	v_pk_mul_f32 v[94:95], v[170:171], v[94:95]
	s_nop 0
	v_cvt_pk_bf16_f32 v94, v94, v95
	ds_write_b32 v172, v94
	v_pk_mul_f32 v[94:95], v[84:85], v[168:169]
	s_nop 0
	v_cvt_pk_bf16_f32 v94, v94, v95
	ds_write_b32 v147, v94
	global_load_dwordx4 v[6:9], v237, s[100:101]
	v_mul_u32_u24_e32 v94, 0x44, v93
	v_lshl_add_u32 v147, v94, 2, v113
	ds_read_b32 v95, v147
	v_mad_u32_u24 v93, v93, s20, v102
	v_lshl_add_u32 v93, v93, 2, v135
	ds_read_b32 v169, v93
	s_waitcnt lgkmcnt(1)
	v_lshlrev_b32_e32 v94, 16, v95
	v_and_b32_e32 v95, 0xffff0000, v95
	v_pk_add_f32 v[170:171], v[94:95], 1.0 op_sel_hi:[1,0] neg_lo:[1,0] neg_hi:[1,0]
	s_waitcnt lgkmcnt(0)
	v_lshlrev_b32_e32 v168, 16, v169
	v_pk_mul_f32 v[84:85], v[84:85], v[170:171]
	v_and_b32_e32 v169, 0xffff0000, v169
	v_max_f32_e32 v170, 0xda24260, v84
	v_max_f32_e32 v171, 0xda24260, v85
	v_rcp_f32_e32 v170, v170
	v_rcp_f32_e32 v171, v171
	s_nop 0
	v_pk_mul_f32 v[94:95], v[170:171], v[94:95]
	s_nop 0
	v_cvt_pk_bf16_f32 v94, v94, v95
	ds_write_b32 v147, v94
	v_pk_mul_f32 v[94:95], v[84:85], v[168:169]
	s_nop 0
	v_cvt_pk_bf16_f32 v94, v94, v95
	ds_write_b32 v93, v94
	v_mul_u32_u24_e32 v93, 0x44, v92
	v_lshl_add_u32 v147, v93, 2, v113
	ds_read_b32 v93, v147
	v_mad_u32_u24 v94, v92, s20, v102
	v_lshl_add_u32 v170, v94, 2, v135
	ds_read_b32 v95, v170
	s_waitcnt lgkmcnt(1)
	v_lshlrev_b32_e32 v92, 16, v93
	v_and_b32_e32 v93, 0xffff0000, v93
	v_pk_add_f32 v[168:169], v[92:93], 1.0 op_sel_hi:[1,0] neg_lo:[1,0] neg_hi:[1,0]
	s_waitcnt lgkmcnt(0)
	v_lshlrev_b32_e32 v94, 16, v95
	v_pk_mul_f32 v[84:85], v[84:85], v[168:169]
	v_and_b32_e32 v95, 0xffff0000, v95
	v_max_f32_e32 v168, 0xda24260, v84
	v_max_f32_e32 v169, 0xda24260, v85
	v_rcp_f32_e32 v168, v168
	v_rcp_f32_e32 v169, v169
	s_nop 0
	v_pk_mul_f32 v[92:93], v[168:169], v[92:93]
	s_nop 0
	v_cvt_pk_bf16_f32 v92, v92, v93
	ds_write_b32 v147, v92
	v_pk_mul_f32 v[92:93], v[84:85], v[94:95]
	s_nop 0
	v_cvt_pk_bf16_f32 v92, v92, v93
	ds_write_b32 v170, v92
	global_load_dwordx4 v[18:21], v238, s[100:101]
	v_mul_u32_u24_e32 v92, 0x44, v91
	v_lshl_add_u32 v147, v92, 2, v113
	ds_read_b32 v93, v147
	v_mad_u32_u24 v91, v91, s20, v102
	v_lshl_add_u32 v91, v91, 2, v135
	ds_read_b32 v95, v91
	s_waitcnt lgkmcnt(1)
	v_lshlrev_b32_e32 v92, 16, v93
	v_and_b32_e32 v93, 0xffff0000, v93
	v_pk_add_f32 v[168:169], v[92:93], 1.0 op_sel_hi:[1,0] neg_lo:[1,0] neg_hi:[1,0]
	s_waitcnt lgkmcnt(0)
	v_lshlrev_b32_e32 v94, 16, v95
	v_pk_mul_f32 v[84:85], v[84:85], v[168:169]
	v_and_b32_e32 v95, 0xffff0000, v95
	v_max_f32_e32 v168, 0xda24260, v84
	v_max_f32_e32 v169, 0xda24260, v85
	v_rcp_f32_e32 v168, v168
	v_rcp_f32_e32 v169, v169
	s_nop 0
	v_pk_mul_f32 v[92:93], v[168:169], v[92:93]
	s_nop 0
	v_cvt_pk_bf16_f32 v92, v92, v93
	ds_write_b32 v147, v92
	v_pk_mul_f32 v[92:93], v[84:85], v[94:95]
	s_nop 0
	v_cvt_pk_bf16_f32 v92, v92, v93
	ds_write_b32 v91, v92
	v_mul_u32_u24_e32 v91, 0x44, v90
	v_lshl_add_u32 v147, v91, 2, v113
	ds_read_b32 v91, v147
	v_mad_u32_u24 v92, v90, s20, v102
	v_lshl_add_u32 v168, v92, 2, v135
	ds_read_b32 v93, v168
	s_waitcnt lgkmcnt(1)
	v_lshlrev_b32_e32 v90, 16, v91
	v_and_b32_e32 v91, 0xffff0000, v91
	v_pk_add_f32 v[94:95], v[90:91], 1.0 op_sel_hi:[1,0] neg_lo:[1,0] neg_hi:[1,0]
	s_waitcnt lgkmcnt(0)
	v_lshlrev_b32_e32 v92, 16, v93
	v_pk_mul_f32 v[84:85], v[84:85], v[94:95]
	v_and_b32_e32 v93, 0xffff0000, v93
	v_max_f32_e32 v94, 0xda24260, v84
	v_max_f32_e32 v95, 0xda24260, v85
	v_rcp_f32_e32 v94, v94
	v_rcp_f32_e32 v95, v95
	s_nop 0
	v_pk_mul_f32 v[90:91], v[94:95], v[90:91]
	s_nop 0
	v_cvt_pk_bf16_f32 v90, v90, v91
	ds_write_b32 v147, v90
	v_pk_mul_f32 v[90:91], v[84:85], v[92:93]
	s_nop 0
	v_cvt_pk_bf16_f32 v90, v90, v91
	ds_write_b32 v168, v90
	global_load_dwordx4 v[22:25], v239, s[100:101]
	v_mul_u32_u24_e32 v90, 0x44, v89
	v_lshl_add_u32 v147, v90, 2, v113
	ds_read_b32 v91, v147
	v_mad_u32_u24 v89, v89, s20, v102
	v_lshl_add_u32 v89, v89, 2, v135
	ds_read_b32 v93, v89
	s_waitcnt lgkmcnt(1)
	v_lshlrev_b32_e32 v90, 16, v91
	v_and_b32_e32 v91, 0xffff0000, v91
	v_pk_add_f32 v[94:95], v[90:91], 1.0 op_sel_hi:[1,0] neg_lo:[1,0] neg_hi:[1,0]
	s_waitcnt lgkmcnt(0)
	v_lshlrev_b32_e32 v92, 16, v93
	v_pk_mul_f32 v[84:85], v[84:85], v[94:95]
	v_and_b32_e32 v93, 0xffff0000, v93
	v_max_f32_e32 v94, 0xda24260, v84
	v_max_f32_e32 v95, 0xda24260, v85
	v_rcp_f32_e32 v94, v94
	v_rcp_f32_e32 v95, v95
	s_nop 0
	v_pk_mul_f32 v[90:91], v[94:95], v[90:91]
	s_nop 0
	v_cvt_pk_bf16_f32 v90, v90, v91
	ds_write_b32 v147, v90
	v_pk_mul_f32 v[90:91], v[84:85], v[92:93]
	v_add_u32_e32 v147, v137, v71
	v_cvt_pk_bf16_f32 v90, v90, v91
	ds_write_b32 v89, v90
	v_mul_u32_u24_e32 v89, 0x44, v88
	v_lshl_add_u32 v94, v89, 2, v113
	ds_read_b32 v89, v94
	v_mad_u32_u24 v90, v88, s20, v102
	v_lshl_add_u32 v95, v90, 2, v135
	ds_read_b32 v91, v95
	s_waitcnt lgkmcnt(1)
	v_lshlrev_b32_e32 v88, 16, v89
	v_and_b32_e32 v89, 0xffff0000, v89
	v_pk_add_f32 v[92:93], v[88:89], 1.0 op_sel_hi:[1,0] neg_lo:[1,0] neg_hi:[1,0]
	s_waitcnt lgkmcnt(0)
	v_lshlrev_b32_e32 v90, 16, v91
	v_pk_mul_f32 v[84:85], v[84:85], v[92:93]
	v_and_b32_e32 v91, 0xffff0000, v91
	v_max_f32_e32 v92, 0xda24260, v84
	v_max_f32_e32 v93, 0xda24260, v85
	v_rcp_f32_e32 v92, v92
	v_rcp_f32_e32 v93, v93
	s_nop 0
	v_pk_mul_f32 v[88:89], v[92:93], v[88:89]
	s_nop 0
	v_cvt_pk_bf16_f32 v88, v88, v89
	ds_write_b32 v94, v88
	v_pk_mul_f32 v[88:89], v[84:85], v[90:91]
	s_nop 0
	v_cvt_pk_bf16_f32 v88, v88, v89
	ds_write_b32 v95, v88
	global_load_dwordx4 v[10:13], v240, s[100:101]
	v_mul_u32_u24_e32 v88, 0x44, v87
	v_lshl_add_u32 v94, v88, 2, v113
	ds_read_b32 v89, v94
	v_mad_u32_u24 v87, v87, s20, v102
	v_lshl_add_u32 v87, v87, 2, v135
	ds_read_b32 v91, v87
	s_waitcnt lgkmcnt(1)
	v_lshlrev_b32_e32 v88, 16, v89
	v_and_b32_e32 v89, 0xffff0000, v89
	v_pk_add_f32 v[92:93], v[88:89], 1.0 op_sel_hi:[1,0] neg_lo:[1,0] neg_hi:[1,0]
	s_waitcnt lgkmcnt(0)
	v_lshlrev_b32_e32 v90, 16, v91
	v_pk_mul_f32 v[84:85], v[84:85], v[92:93]
	v_and_b32_e32 v91, 0xffff0000, v91
	v_max_f32_e32 v92, 0xda24260, v84
	v_max_f32_e32 v93, 0xda24260, v85
	v_rcp_f32_e32 v92, v92
	v_rcp_f32_e32 v93, v93
	s_nop 0
	v_pk_mul_f32 v[88:89], v[92:93], v[88:89]
	s_nop 0
	v_cvt_pk_bf16_f32 v88, v88, v89
	ds_write_b32 v94, v88
	v_pk_mul_f32 v[88:89], v[84:85], v[90:91]
	s_nop 0
	v_cvt_pk_bf16_f32 v88, v88, v89
	ds_write_b32 v87, v88
	v_mul_u32_u24_e32 v87, 0x44, v86
	v_lshl_add_u32 v92, v87, 2, v113
	ds_read_b32 v87, v92
	v_mad_u32_u24 v88, v86, s20, v102
	v_lshl_add_u32 v93, v88, 2, v135
	ds_read_b32 v89, v93
	s_waitcnt lgkmcnt(1)
	v_lshlrev_b32_e32 v86, 16, v87
	v_and_b32_e32 v87, 0xffff0000, v87
	v_pk_add_f32 v[90:91], v[86:87], 1.0 op_sel_hi:[1,0] neg_lo:[1,0] neg_hi:[1,0]
	s_waitcnt lgkmcnt(0)
	v_lshlrev_b32_e32 v88, 16, v89
	v_pk_mul_f32 v[84:85], v[84:85], v[90:91]
	v_and_b32_e32 v89, 0xffff0000, v89
	v_max_f32_e32 v90, 0xda24260, v84
	v_max_f32_e32 v91, 0xda24260, v85
	v_rcp_f32_e32 v90, v90
	v_rcp_f32_e32 v91, v91
	v_pk_mul_f32 v[84:85], v[84:85], v[88:89]
	v_pk_mul_f32 v[86:87], v[90:91], v[86:87]
	s_nop 0
	v_cvt_pk_bf16_f32 v86, v86, v87
	v_cvt_pk_bf16_f32 v84, v84, v85
	ds_write_b32 v92, v86
	ds_write_b32 v93, v84
	global_load_dwordx4 v[14:17], v241, s[100:101]
	s_waitcnt lgkmcnt(0)
	s_barrier
	ds_read_b128 v[84:87], v136
	ds_read_b128 v[88:91], v147
	ds_read_b128 v[92:95], v147 offset:4352
	ds_read_b128 v[168:171], v147 offset:8704
	ds_read_b128 v[172:175], v176
	s_waitcnt lgkmcnt(3)
	v_mfma_f32_16x16x32_bf16 v[88:91], v[84:87], v[88:91], 0
	s_waitcnt lgkmcnt(2)
	v_mfma_f32_16x16x32_bf16 v[92:95], v[84:87], v[92:95], 0
	s_waitcnt lgkmcnt(1)
	v_mfma_f32_16x16x32_bf16 v[168:171], v[84:87], v[168:171], 0
	s_waitcnt lgkmcnt(0)
	v_mfma_f32_16x16x32_bf16 v[84:87], v[84:87], v[172:175], 0
	ds_read_b128 v[172:175], v136 offset:64
	ds_read_b128 v[198:201], v147 offset:64
	s_waitcnt lgkmcnt(0)
	v_mfma_f32_16x16x32_bf16 v[88:91], v[172:175], v[198:201], v[88:91]
	ds_read_b128 v[198:201], v147 offset:4416
	s_waitcnt lgkmcnt(0)
	v_mfma_f32_16x16x32_bf16 v[92:95], v[172:175], v[198:201], v[92:95]
	ds_read_b128 v[198:201], v147 offset:8768
	s_waitcnt lgkmcnt(0)
	v_mfma_f32_16x16x32_bf16 v[168:171], v[172:175], v[198:201], v[168:171]
	ds_read_b128 v[198:201], v176 offset:64
	s_waitcnt lgkmcnt(0)
	v_mfma_f32_16x16x32_bf16 v[84:87], v[172:175], v[198:201], v[84:87]
	ds_read_b128 v[172:175], v136 offset:128
	ds_read_b128 v[198:201], v147 offset:128
	s_waitcnt lgkmcnt(0)
	global_load_dwordx4 v[26:29], v242, s[100:101]
	v_mfma_f32_16x16x32_bf16 v[88:91], v[172:175], v[198:201], v[88:91]
	ds_read_b128 v[198:201], v147 offset:4480
	s_waitcnt lgkmcnt(0)
	v_mfma_f32_16x16x32_bf16 v[92:95], v[172:175], v[198:201], v[92:95]
	ds_read_b128 v[198:201], v147 offset:8832
	s_waitcnt lgkmcnt(0)
	v_mfma_f32_16x16x32_bf16 v[168:171], v[172:175], v[198:201], v[168:171]
	ds_read_b128 v[198:201], v176 offset:128
	s_waitcnt lgkmcnt(0)
	v_mfma_f32_16x16x32_bf16 v[84:87], v[172:175], v[198:201], v[84:87]
	ds_read_b128 v[172:175], v136 offset:192
	ds_read_b128 v[198:201], v147 offset:192
	s_waitcnt lgkmcnt(0)
	v_mfma_f32_16x16x32_bf16 v[88:91], v[172:175], v[198:201], v[88:91]
	ds_read_b128 v[198:201], v147 offset:4544
	s_waitcnt lgkmcnt(0)
	v_mfma_f32_16x16x32_bf16 v[92:95], v[172:175], v[198:201], v[92:95]
	ds_read_b128 v[198:201], v147 offset:8896
	s_nop 3
	v_cvt_pk_bf16_f32 v88, v88, s0
	v_cvt_pk_bf16_f32 v89, v89, s0
	s_waitcnt lgkmcnt(0)
	v_mfma_f32_16x16x32_bf16 v[168:171], v[172:175], v[198:201], v[168:171]
	ds_read_b128 v[198:201], v176 offset:192
	v_cvt_pk_bf16_f32 v90, v90, s0
	v_cvt_pk_bf16_f32 v91, v91, s0
	v_cndmask_b32_e64 v88, 0, v88, s[42:43]
	v_cndmask_b32_e64 v89, 0, v89, s[44:45]
	v_cndmask_b32_e64 v90, 0, v90, s[46:47]
	v_cndmask_b32_e64 v91, 0, v91, s[48:49]
	s_waitcnt lgkmcnt(0)
	v_mfma_f32_16x16x32_bf16 v[84:87], v[172:175], v[198:201], v[84:87]
	v_perm_b32 v88, v89, v88, s21
	v_perm_b32 v89, v91, v90, s21
	v_add_u32_e32 v90, v138, v75
	global_load_dwordx4 v[30:33], v243, s[100:101]
	ds_write_b64 v90, v[88:89]
	v_cvt_pk_bf16_f32 v88, v92, s0
	v_cvt_pk_bf16_f32 v89, v93, s0
	v_cvt_pk_bf16_f32 v91, v94, s0
	v_cvt_pk_bf16_f32 v92, v95, s0
	v_cndmask_b32_e64 v88, 0, v88, s[50:51]
	v_cndmask_b32_e64 v89, 0, v89, s[52:53]
	v_cndmask_b32_e64 v91, 0, v91, s[54:55]
	v_cndmask_b32_e64 v92, 0, v92, s[56:57]
	v_perm_b32 v88, v89, v88, s21
	v_perm_b32 v89, v92, v91, s21
	ds_write_b64 v90, v[88:89] offset:2304
	v_cvt_pk_bf16_f32 v88, v168, s0
	v_cvt_pk_bf16_f32 v89, v169, s0
	v_cvt_pk_bf16_f32 v91, v170, s0
	v_cvt_pk_bf16_f32 v92, v171, s0
	v_cvt_pk_bf16_f32 v84, v84, s0
	v_cvt_pk_bf16_f32 v85, v85, s0
	v_cvt_pk_bf16_f32 v86, v86, s0
	v_cvt_pk_bf16_f32 v87, v87, s0
	v_cndmask_b32_e64 v88, 0, v88, s[58:59]
	v_cndmask_b32_e64 v89, 0, v89, s[60:61]
	v_cndmask_b32_e64 v91, 0, v91, s[62:63]
	v_cndmask_b32_e64 v92, 0, v92, s[64:65]
	v_cndmask_b32_e64 v84, 0, v84, s[66:67]
	v_cndmask_b32_e64 v85, 0, v85, s[68:69]
	v_cndmask_b32_e64 v86, 0, v86, s[70:71]
	v_cndmask_b32_e64 v87, 0, v87, s[72:73]
	v_perm_b32 v88, v89, v88, s21
	v_perm_b32 v89, v92, v91, s21
	v_perm_b32 v84, v85, v84, s21
	v_perm_b32 v85, v87, v86, s21
	v_add_u32_e32 v86, v138, v96
	ds_write_b64 v90, v[88:89] offset:4608
	ds_write_b64 v86, v[84:85]
	s_waitcnt lgkmcnt(0)
	s_barrier
	ds_read_b64_tr_b16 v[84:85], v164
	ds_read_b64_tr_b16 v[86:87], v164 offset:1088
	ds_read_b128 v[88:91], v139
	ds_read_b128 v[92:95], v140
	s_waitcnt lgkmcnt(1)
	v_mfma_f32_16x16x32_bf16 v[88:91], v[88:91], v[84:87], 0
	v_add_u32_e32 v147, v106, v71
	v_add_u32_e32 v176, v106, v73
	s_waitcnt lgkmcnt(0)
	v_mfma_f32_16x16x32_bf16 v[88:91], v[92:95], v[84:87], v[88:91]
	ds_read_b128 v[92:95], v141
	ds_read_b128 v[168:171], v142
	s_waitcnt lgkmcnt(1)
	v_mfma_f32_16x16x32_bf16 v[92:95], v[92:95], v[84:87], 0
	s_waitcnt lgkmcnt(0)
	v_mfma_f32_16x16x32_bf16 v[92:95], v[168:171], v[84:87], v[92:95]
	ds_read_b128 v[168:171], v143
	ds_read_b128 v[172:175], v144
	s_waitcnt lgkmcnt(1)
	v_mfma_f32_16x16x32_bf16 v[168:171], v[168:171], v[84:87], 0
	s_waitcnt lgkmcnt(0)
	v_mfma_f32_16x16x32_bf16 v[168:171], v[172:175], v[84:87], v[168:171]
	ds_read_b128 v[172:175], v145
	ds_read_b128 v[198:201], v152
	s_waitcnt lgkmcnt(1)
	v_mfma_f32_16x16x32_bf16 v[172:175], v[172:175], v[84:87], 0
	s_waitcnt lgkmcnt(0)
	v_mfma_f32_16x16x32_bf16 v[84:87], v[198:201], v[84:87], v[172:175]
	s_nop 5
	ds_read_b64_tr_b16 v[172:173], v165
	ds_read_b64_tr_b16 v[174:175], v165 offset:1088
	ds_read_b128 v[198:201], v153
	ds_read_b128 v[202:205], v154
	s_waitcnt lgkmcnt(1)
	v_mfma_f32_16x16x32_bf16 v[88:91], v[198:201], v[172:175], v[88:91]
	s_waitcnt lgkmcnt(0)
	v_mfma_f32_16x16x32_bf16 v[88:91], v[202:205], v[172:175], v[88:91]
	ds_read_b128 v[198:201], v155
	ds_read_b128 v[202:205], v156
	s_waitcnt lgkmcnt(1)
	v_mfma_f32_16x16x32_bf16 v[92:95], v[198:201], v[172:175], v[92:95]
	s_waitcnt lgkmcnt(0)
	v_mfma_f32_16x16x32_bf16 v[92:95], v[202:205], v[172:175], v[92:95]
	ds_read_b128 v[198:201], v157
	ds_read_b128 v[202:205], v158
	s_waitcnt lgkmcnt(1)
	v_mfma_f32_16x16x32_bf16 v[168:171], v[198:201], v[172:175], v[168:171]
	s_waitcnt lgkmcnt(0)
	v_mfma_f32_16x16x32_bf16 v[168:171], v[202:205], v[172:175], v[168:171]
	ds_read_b128 v[198:201], v159
	ds_read_b128 v[202:205], v160
	s_waitcnt lgkmcnt(1)
	v_mfma_f32_16x16x32_bf16 v[84:87], v[198:201], v[172:175], v[84:87]
	s_waitcnt lgkmcnt(0)
	v_mfma_f32_16x16x32_bf16 v[84:87], v[202:205], v[172:175], v[84:87]
	ds_read_b128 v[172:175], v147
	ds_read_b128 v[198:201], v147 offset:4352
	ds_read_b128 v[202:205], v147 offset:8704
	ds_read_b128 v[246:249], v176
	s_lshl_b32 s80, s14, 8
	ds_read_b128 v[250:253], v147 offset:64
	s_waitcnt vmcnt(15) lgkmcnt(4)
	v_mfma_f32_16x16x32_bf16 v[88:91], v[172:175], v[62:65], v[88:91]
	ds_read_b128 v[172:175], v147 offset:4416
	s_waitcnt lgkmcnt(4)
	v_mfma_f32_16x16x32_bf16 v[92:95], v[198:201], v[62:65], v[92:95]
	ds_read_b128 v[198:201], v147 offset:8768
	s_waitcnt lgkmcnt(4)
	v_mfma_f32_16x16x32_bf16 v[168:171], v[202:205], v[62:65], v[168:171]
	ds_read_b128 v[202:205], v176 offset:64
	s_waitcnt lgkmcnt(4)
	v_mfma_f32_16x16x32_bf16 v[84:87], v[246:249], v[62:65], v[84:87]
	ds_read_b128 v[246:249], v147 offset:128
	s_waitcnt vmcnt(14) lgkmcnt(4)
	v_mfma_f32_16x16x32_bf16 v[88:91], v[250:253], v[58:61], v[88:91]
	ds_read_b128 v[250:253], v147 offset:4480
	s_waitcnt lgkmcnt(4)
	v_mfma_f32_16x16x32_bf16 v[92:95], v[172:175], v[58:61], v[92:95]
	ds_read_b128 v[172:175], v147 offset:8832
	s_waitcnt lgkmcnt(4)
	v_mfma_f32_16x16x32_bf16 v[168:171], v[198:201], v[58:61], v[168:171]
	ds_read_b128 v[198:201], v176 offset:128
	s_waitcnt lgkmcnt(4)
	v_mfma_f32_16x16x32_bf16 v[84:87], v[202:205], v[58:61], v[84:87]
	ds_read_b128 v[202:205], v147 offset:192
	s_waitcnt vmcnt(13) lgkmcnt(4)
	v_mfma_f32_16x16x32_bf16 v[88:91], v[246:249], v[54:57], v[88:91]
	ds_read_b128 v[246:249], v147 offset:4544
	s_waitcnt lgkmcnt(4)
	v_mfma_f32_16x16x32_bf16 v[92:95], v[250:253], v[54:57], v[92:95]
	ds_read_b128 v[250:253], v147 offset:8896
	s_waitcnt lgkmcnt(4)
	v_mfma_f32_16x16x32_bf16 v[168:171], v[172:175], v[54:57], v[168:171]
	ds_read_b128 v[172:175], v176 offset:192
	s_waitcnt lgkmcnt(4)
	v_mfma_f32_16x16x32_bf16 v[84:87], v[198:201], v[54:57], v[84:87]
	ds_read_b128 v[198:201], v147 offset:17408
	s_waitcnt vmcnt(12) lgkmcnt(4)
	v_mfma_f32_16x16x32_bf16 v[88:91], v[202:205], v[50:53], v[88:91]
	ds_read_b128 v[202:205], v147 offset:21760
	s_waitcnt lgkmcnt(4)
	v_mfma_f32_16x16x32_bf16 v[92:95], v[246:249], v[50:53], v[92:95]
	ds_read_b128 v[246:249], v147 offset:26112
	s_waitcnt lgkmcnt(4)
	v_mfma_f32_16x16x32_bf16 v[168:171], v[250:253], v[50:53], v[168:171]
	ds_read_b128 v[250:253], v176 offset:17408
	s_waitcnt lgkmcnt(4)
	v_mfma_f32_16x16x32_bf16 v[84:87], v[172:175], v[50:53], v[84:87]
	ds_read_b128 v[172:175], v147 offset:17472
	s_waitcnt vmcnt(11) lgkmcnt(4)
	v_mfma_f32_16x16x32_bf16 v[88:91], v[198:201], v[46:49], v[88:91]
	ds_read_b128 v[198:201], v147 offset:21824
	s_waitcnt lgkmcnt(4)
	v_mfma_f32_16x16x32_bf16 v[92:95], v[202:205], v[46:49], v[92:95]
	ds_read_b128 v[202:205], v147 offset:26176
	s_waitcnt lgkmcnt(4)
	v_mfma_f32_16x16x32_bf16 v[168:171], v[246:249], v[46:49], v[168:171]
	ds_read_b128 v[246:249], v176 offset:17472
	s_waitcnt lgkmcnt(4)
	v_mfma_f32_16x16x32_bf16 v[84:87], v[250:253], v[46:49], v[84:87]
	ds_read_b128 v[250:253], v147 offset:17536
	s_waitcnt vmcnt(10) lgkmcnt(4)
	v_mfma_f32_16x16x32_bf16 v[88:91], v[172:175], v[42:45], v[88:91]
	ds_read_b128 v[172:175], v147 offset:21888
	s_waitcnt lgkmcnt(4)
	v_mfma_f32_16x16x32_bf16 v[92:95], v[198:201], v[42:45], v[92:95]
	ds_read_b128 v[198:201], v147 offset:26240
	s_waitcnt lgkmcnt(4)
	v_mfma_f32_16x16x32_bf16 v[168:171], v[202:205], v[42:45], v[168:171]
	ds_read_b128 v[202:205], v176 offset:17536
	s_waitcnt lgkmcnt(4)
	v_mfma_f32_16x16x32_bf16 v[84:87], v[246:249], v[42:45], v[84:87]
	ds_read_b128 v[246:249], v147 offset:17600
	s_waitcnt vmcnt(9) lgkmcnt(4)
	v_mfma_f32_16x16x32_bf16 v[88:91], v[250:253], v[38:41], v[88:91]
	ds_read_b128 v[250:253], v147 offset:21952
	s_waitcnt lgkmcnt(4)
	v_mfma_f32_16x16x32_bf16 v[92:95], v[172:175], v[38:41], v[92:95]
	ds_read_b128 v[172:175], v147 offset:26304
	s_waitcnt lgkmcnt(4)
	v_mfma_f32_16x16x32_bf16 v[168:171], v[198:201], v[38:41], v[168:171]
	ds_read_b128 v[198:201], v176 offset:17600
	s_waitcnt lgkmcnt(4)
	v_mfma_f32_16x16x32_bf16 v[84:87], v[202:205], v[38:41], v[84:87]
	v_lshl_add_u64 v[58:59], vcc, 0, v[76:77]
	s_waitcnt vmcnt(8) lgkmcnt(3)
	v_mfma_f32_16x16x32_bf16 v[42:45], v[246:249], v[34:37], v[88:91]
	s_waitcnt lgkmcnt(2)
	v_mfma_f32_16x16x32_bf16 v[46:49], v[250:253], v[34:37], v[92:95]
	s_waitcnt lgkmcnt(1)
	v_mfma_f32_16x16x32_bf16 v[50:53], v[172:175], v[34:37], v[168:171]
	s_waitcnt lgkmcnt(0)
	v_mfma_f32_16x16x32_bf16 v[38:41], v[198:201], v[34:37], v[84:87]
	v_lshlrev_b64 v[34:35], 8, v[58:59]
	v_lshl_add_u64 v[34:35], s[16:17], 0, v[34:35]
	v_lshl_add_u64 v[34:35], v[34:35], 0, v[0:1]
	s_mov_b64 s[16:17], 0x10000000
	v_lshl_add_u64 v[36:37], v[34:35], 0, s[16:17]
	v_add_co_u32_e32 v34, vcc, s15, v34
	v_lshlrev_b64 v[58:59], 11, v[58:59]
	s_nop 0
	v_addc_co_u32_e32 v35, vcc, 0, v35, vcc
	global_load_dwordx4 v[54:57], v[34:35], off
	s_nop 0
	global_load_dwordx4 v[34:37], v[36:37], off offset:16
	s_barrier
	ds_write2_b32 v166, v42, v43 offset1:132
	v_add_u32_e32 v42, 0x400, v166
	ds_write2_b32 v42, v44, v45 offset0:8 offset1:140
	v_add_u32_e32 v42, 0x2000, v166
	ds_write2_b32 v42, v46, v47 offset0:64 offset1:196
	v_add_u32_e32 v42, 0x2400, v166
	ds_write2_b32 v42, v48, v49 offset0:72 offset1:204
	v_add_u32_e32 v42, 0x4200, v166
	ds_write2_b32 v42, v50, v51 offset1:132
	v_add_u32_e32 v42, 0x4600, v166
	ds_write2_b32 v42, v52, v53 offset0:8 offset1:140
	v_add_u32_e32 v42, 0x6200, v166
	ds_write2_b32 v42, v38, v39 offset0:64 offset1:196
	v_add_u32_e32 v38, 0x6600, v166
	ds_write2_b32 v38, v40, v41 offset0:72 offset1:204
	s_waitcnt lgkmcnt(0)
	s_barrier
	ds_read_b128 v[50:53], v162
	ds_read_b128 v[46:49], v162 offset:16
	ds_read_b128 v[42:45], v162 offset:32
	ds_read_b128 v[38:41], v162 offset:48
	v_lshl_add_u64 v[58:59], s[74:75], 0, v[58:59]
	s_waitcnt lgkmcnt(3)
	v_pk_mul_f32 v[60:61], v[52:53], v[52:53]
	v_pk_mul_f32 v[62:63], v[50:51], v[50:51]
	v_lshl_add_u64 v[58:59], v[58:59], 0, s[80:81]
	v_pk_mov_b32 v[64:65], v[62:63], v[60:61] op_sel:[1,0]
	v_mov_b32_e32 v63, v61
	v_pk_add_f32 v[60:61], v[64:65], v[62:63]
	s_waitcnt lgkmcnt(2)
	v_pk_mul_f32 v[62:63], v[48:49], v[48:49]
	v_pk_mul_f32 v[64:65], v[46:47], v[46:47]
	v_pk_add_f32 v[60:61], v[60:61], v[60:61] op_sel:[0,1] op_sel_hi:[1,0]
	v_pk_mov_b32 v[84:85], v[64:65], v[62:63] op_sel:[1,0]
	v_mov_b32_e32 v65, v63
	v_pk_add_f32 v[62:63], v[84:85], v[64:65]
	s_waitcnt lgkmcnt(0)
	v_mul_f32_e32 v64, v38, v38
	v_mul_f32_e32 v65, v39, v39
	v_pk_add_f32 v[62:63], v[62:63], v[62:63] op_sel:[0,1] op_sel_hi:[1,0]
	v_mov_b32_e32 v61, v64
	v_mov_b32_e32 v63, v65
	v_pk_add_f32 v[60:61], v[60:61], v[62:63]
	v_mul_f32_e32 v62, v43, v43
	v_mul_f32_e32 v64, v45, v45
	v_mul_f32_e32 v84, v40, v40
	v_mul_f32_e32 v85, v41, v41
	v_pk_fma_f32 v[62:63], v[42:43], v[42:43], v[62:63] op_sel_hi:[1,1,0]
	v_pk_fma_f32 v[64:65], v[44:45], v[44:45], v[64:65] op_sel_hi:[1,1,0]
	v_mov_b32_e32 v63, v84
	v_mov_b32_e32 v65, v85
	v_pk_add_f32 v[62:63], v[62:63], v[64:65]
	v_lshl_add_u64 v[86:87], v[58:59], 0, v[0:1]
	v_pk_add_f32 v[60:61], v[60:61], v[62:63]
	s_waitcnt vmcnt(1)
	v_lshlrev_b32_e32 v92, 16, v54
	v_add_f32_e32 v60, v60, v61
	ds_bpermute_b32 v61, v97, v60
	v_and_b32_e32 v93, 0xffff0000, v54
	v_lshlrev_b32_e32 v94, 16, v55
	v_and_b32_e32 v95, 0xffff0000, v55
	v_lshlrev_b32_e32 v88, 16, v56
	s_waitcnt lgkmcnt(0)
	v_add_f32_e32 v60, v60, v61
	ds_bpermute_b32 v61, v98, v60
	v_and_b32_e32 v89, 0xffff0000, v56
	v_lshlrev_b32_e32 v90, 16, v57
	v_and_b32_e32 v91, 0xffff0000, v57
	s_waitcnt lgkmcnt(0)
	v_add_f32_e32 v60, v60, v61
	ds_bpermute_b32 v61, v163, v60
	s_waitcnt lgkmcnt(0)
	v_add_f32_e32 v60, v60, v61
	v_fmamk_f32 v60, v60, 0x3c000000, v178
	v_cmp_gt_f32_e32 vcc, s22, v60
	v_mul_f32_e32 v61, 0x4b800000, v60
	s_nop 0
	v_cndmask_b32_e32 v60, v60, v61, vcc
	v_rsq_f32_e32 v60, v60
	s_nop 0
	v_mul_f32_e32 v61, 0x45800000, v60
	v_cndmask_b32_e32 v84, v60, v61, vcc
	v_pk_mul_f32 v[52:53], v[52:53], v[84:85] op_sel_hi:[1,0]
	v_pk_mul_f32 v[50:51], v[50:51], v[84:85] op_sel_hi:[1,0]
	v_pk_mul_f32 v[48:49], v[48:49], v[84:85] op_sel_hi:[1,0]
	v_pk_mul_f32 v[46:47], v[46:47], v[84:85] op_sel_hi:[1,0]
	v_pk_mul_f32 v[44:45], v[44:45], v[84:85] op_sel_hi:[1,0]
	v_pk_mul_f32 v[42:43], v[42:43], v[84:85] op_sel_hi:[1,0]
	v_pk_mul_f32 v[40:41], v[40:41], v[84:85] op_sel_hi:[1,0]
	v_pk_mul_f32 v[38:39], v[38:39], v[84:85] op_sel_hi:[1,0]
	s_and_b64 vcc, exec, s[12:13]
	v_pk_mul_f32 v[38:39], v[232:233], v[38:39]
	v_pk_mul_f32 v[42:43], v[228:229], v[42:43]
	v_pk_mul_f32 v[46:47], v[224:225], v[46:47]
	v_pk_mul_f32 v[50:51], v[220:221], v[50:51]
	v_pk_mul_f32 v[52:53], v[222:223], v[52:53]
	v_pk_mul_f32 v[48:49], v[226:227], v[48:49]
	v_pk_mul_f32 v[52:53], v[52:53], v[94:95]
	v_pk_mul_f32 v[50:51], v[50:51], v[92:93]
	v_pk_mul_f32 v[62:63], v[48:49], v[90:91]
	v_pk_mul_f32 v[48:49], v[46:47], v[88:89]
	v_cvt_pk_bf16_f32 v46, v50, v51
	v_cvt_pk_bf16_f32 v47, v52, v53
	v_cvt_pk_bf16_f32 v48, v48, v49
	v_cvt_pk_bf16_f32 v49, v62, v63
	global_store_dwordx4 v[86:87], v[46:49], off offset:1024
	v_pk_mul_f32 v[44:45], v[230:231], v[44:45]
	v_pk_mul_f32 v[40:41], v[234:235], v[40:41]
	s_waitcnt vmcnt(1)
	v_lshlrev_b32_e32 v46, 16, v34
	v_and_b32_e32 v47, 0xffff0000, v34
	v_lshlrev_b32_e32 v34, 16, v35
	v_and_b32_e32 v35, 0xffff0000, v35
	v_lshlrev_b32_e32 v48, 16, v36
	v_and_b32_e32 v49, 0xffff0000, v36
	v_lshlrev_b32_e32 v36, 16, v37
	v_and_b32_e32 v37, 0xffff0000, v37
	v_pk_mul_f32 v[44:45], v[44:45], v[34:35]
	v_pk_mul_f32 v[34:35], v[42:43], v[46:47]
	v_pk_mul_f32 v[40:41], v[40:41], v[36:37]
	v_pk_mul_f32 v[36:37], v[38:39], v[48:49]
	v_cvt_pk_bf16_f32 v34, v34, v35
	v_cvt_pk_bf16_f32 v35, v44, v45
	v_cvt_pk_bf16_f32 v36, v36, v37
	v_cvt_pk_bf16_f32 v37, v40, v41
	global_store_dwordx4 v[86:87], v[34:37], off offset:1040
	s_barrier
	s_cbranch_vccnz .LBB0_455
.LBB0_445:
	s_add_i32 s28, s29, s2
	s_cmpk_gt_i32 s28, 0x7ff
	s_cselect_b64 s[12:13], -1, 0
	s_waitcnt vmcnt(11)
	ds_write_b128 v109, v[2:5]
	ds_write_b128 v109, v[2:5] offset:17408
	s_waitcnt vmcnt(10)
	ds_write_b128 v109, v[6:9] offset:34816
	s_waitcnt vmcnt(9)
	ds_write_b128 v109, v[18:21] offset:52224
	s_waitcnt vmcnt(8)
	ds_write_b128 v110, v[22:25]
	s_waitcnt vmcnt(7)
	ds_write_b128 v111, v[10:13]
	ds_write_b128 v111, v[10:13] offset:17408
	s_waitcnt vmcnt(6)
	ds_write_b128 v111, v[14:17] offset:34816
	s_waitcnt vmcnt(5)
	ds_write_b128 v111, v[26:29] offset:52224
	s_waitcnt vmcnt(4)
	ds_write_b128 v112, v[30:33]
	s_waitcnt lgkmcnt(0)
	s_barrier
	s_cmpk_lt_i32 s28, 0x800
	s_cselect_b32 s14, s28, s29
	s_lshr_b32 s15, s14, 2
	s_lshl_b32 s15, s15, 14
	s_and_b32 s14, s14, 3
	s_lshl_b32 s14, s14, 23
	s_add_u32 s14, s14, s15
	s_add_u32 s14, s14, 0x8000000
	s_add_u32 s100, s86, s14
	s_addc_u32 s101, s87, 0
	s_and_b32 s14, s29, 3
	s_lshl_b32 s14, s14, 9
	s_mov_b32 s15, 0
	v_lshl_add_u64 v[244:245], v[80:81], 0, s[14:15]
	global_load_dwordx4 v[220:223], v[244:245], off
	global_load_dwordx4 v[224:227], v[244:245], off offset:16
	global_load_dwordx4 v[228:231], v[244:245], off offset:32
	global_load_dwordx4 v[232:235], v[244:245], off offset:48
.LBB0_447:
	s_movk_i32 s14, 0x8000
	v_add_co_u32_e32 v34, vcc, s14, v82
	v_readfirstlane_b32 s14, v70
	s_nop 0
	v_addc_co_u32_e32 v35, vcc, -1, v83, vcc
	global_load_dwordx4 v[62:65], v[34:35], off offset:-192
	s_bfe_u32 s16, s14, 0x20006
	s_lshl_b32 s14, s16, 4
	s_or_b32 s15, s14, 15
	v_mov_b32_e32 v197, s15
	v_mov_b32_e32 v200, s14
	v_cndmask_b32_e64 v173, v197, v200, s[40:41]
	v_or_b32_e32 v172, s14, v115
	v_or_b32_e32 v171, s14, v118
	v_or_b32_e32 v170, s14, v119
	v_mad_u32_u24 v84, v173, s18, v113
	v_mad_u32_u24 v85, v172, s18, v113
	v_mad_u32_u24 v86, v171, s18, v113
	v_mad_u32_u24 v87, v170, s18, v113
	v_or_b32_e32 v169, s14, v120
	v_or_b32_e32 v168, s14, v121
	v_or_b32_e32 v95, s14, v122
	v_or_b32_e32 v94, s14, v123
	v_mad_u32_u24 v88, v169, s18, v113
	v_mad_u32_u24 v89, v168, s18, v113
	v_mad_u32_u24 v90, v95, s18, v113
	v_mad_u32_u24 v91, v94, s18, v113
	ds_read_b32 v92, v84
	ds_read_b32 v93, v85
	ds_read_b32 v147, v86
	ds_read_b32 v174, v87
	ds_read_b32 v175, v88
	ds_read_b32 v176, v89
	ds_read_b32 v177, v90
	ds_read_b32 v199, v91
	global_load_dwordx4 v[58:61], v[34:35], off offset:-128
	s_waitcnt lgkmcnt(7)
	v_lshlrev_b32_e32 v84, 16, v92
	v_and_b32_e32 v85, 0xffff0000, v92
	s_waitcnt lgkmcnt(6)
	v_lshlrev_b32_e32 v86, 16, v93
	v_and_b32_e32 v87, 0xffff0000, v93
	s_waitcnt lgkmcnt(5)
	v_lshlrev_b32_e32 v88, 16, v147
	v_and_b32_e32 v89, 0xffff0000, v147
	v_pk_add_f32 v[84:85], v[84:85], 1.0 op_sel_hi:[1,0] neg_lo:[1,0] neg_hi:[1,0]
	v_pk_add_f32 v[86:87], v[86:87], 1.0 op_sel_hi:[1,0] neg_lo:[1,0] neg_hi:[1,0]
	s_waitcnt lgkmcnt(4)
	v_lshlrev_b32_e32 v90, 16, v174
	v_and_b32_e32 v91, 0xffff0000, v174
	v_pk_mul_f32 v[84:85], v[84:85], v[86:87]
	v_pk_add_f32 v[86:87], v[88:89], 1.0 op_sel_hi:[1,0] neg_lo:[1,0] neg_hi:[1,0]
	s_waitcnt lgkmcnt(3)
	v_lshlrev_b32_e32 v92, 16, v175
	v_and_b32_e32 v93, 0xffff0000, v175
	v_pk_mul_f32 v[84:85], v[84:85], v[86:87]
	v_pk_add_f32 v[86:87], v[90:91], 1.0 op_sel_hi:[1,0] neg_lo:[1,0] neg_hi:[1,0]
	v_or_b32_e32 v91, s14, v127
	v_pk_mul_f32 v[84:85], v[84:85], v[86:87]
	v_pk_add_f32 v[86:87], v[92:93], 1.0 op_sel_hi:[1,0] neg_lo:[1,0] neg_hi:[1,0]
	v_or_b32_e32 v93, s14, v124
	v_pk_mul_f32 v[84:85], v[84:85], v[86:87]
	s_waitcnt lgkmcnt(2)
	v_lshlrev_b32_e32 v86, 16, v176
	v_and_b32_e32 v87, 0xffff0000, v176
	v_pk_add_f32 v[174:175], v[86:87], 1.0 op_sel_hi:[1,0] neg_lo:[1,0] neg_hi:[1,0]
	v_cndmask_b32_e64 v86, v200, v197, s[40:41]
	s_waitcnt lgkmcnt(1)
	v_lshlrev_b32_e32 v176, 16, v177
	v_and_b32_e32 v177, 0xffff0000, v177
	v_mad_u32_u24 v201, v93, s18, v113
	v_or_b32_e32 v92, s14, v126
	v_or_b32_e32 v90, s14, v128
	v_or_b32_e32 v89, s14, v129
	v_or_b32_e32 v88, s14, v130
	v_or_b32_e32 v87, s14, v131
	v_mad_u32_u24 v197, v86, s18, v113
	s_waitcnt lgkmcnt(0)
	v_lshlrev_b32_e32 v198, 16, v199
	v_and_b32_e32 v199, 0xffff0000, v199
	v_mad_u32_u24 v202, v92, s18, v113
	v_mad_u32_u24 v203, v91, s18, v113
	v_mad_u32_u24 v204, v90, s18, v113
	v_mad_u32_u24 v205, v89, s18, v113
	v_mad_u32_u24 v206, v88, s18, v113
	v_mad_u32_u24 v207, v87, s18, v113
	ds_read_b32 v201, v201
	ds_read_b32 v208, v202
	ds_read_b32 v209, v203
	ds_read_b32 v210, v204
	ds_read_b32 v211, v205
	ds_read_b32 v212, v206
	ds_read_b32 v213, v207
	ds_read_b32 v197, v197
	global_load_dwordx4 v[54:57], v[34:35], off offset:-64
	v_pk_mul_f32 v[84:85], v[84:85], v[174:175]
	v_pk_add_f32 v[174:175], v[176:177], 1.0 op_sel_hi:[1,0] neg_lo:[1,0] neg_hi:[1,0]
	s_waitcnt lgkmcnt(7)
	v_lshlrev_b32_e32 v200, 16, v201
	v_and_b32_e32 v201, 0xffff0000, v201
	v_pk_mul_f32 v[84:85], v[84:85], v[174:175]
	v_pk_add_f32 v[174:175], v[198:199], 1.0 op_sel_hi:[1,0] neg_lo:[1,0] neg_hi:[1,0]
	s_waitcnt lgkmcnt(6)
	v_lshlrev_b32_e32 v202, 16, v208
	v_and_b32_e32 v203, 0xffff0000, v208
	v_pk_mul_f32 v[84:85], v[84:85], v[174:175]
	v_pk_add_f32 v[174:175], v[200:201], 1.0 op_sel_hi:[1,0] neg_lo:[1,0] neg_hi:[1,0]
	s_waitcnt lgkmcnt(5)
	v_lshlrev_b32_e32 v204, 16, v209
	v_and_b32_e32 v205, 0xffff0000, v209
	v_pk_mul_f32 v[84:85], v[84:85], v[174:175]
	v_pk_add_f32 v[174:175], v[202:203], 1.0 op_sel_hi:[1,0] neg_lo:[1,0] neg_hi:[1,0]
	s_waitcnt lgkmcnt(4)
	v_lshlrev_b32_e32 v206, 16, v210
	v_and_b32_e32 v207, 0xffff0000, v210
	v_pk_mul_f32 v[84:85], v[84:85], v[174:175]
	v_pk_add_f32 v[174:175], v[204:205], 1.0 op_sel_hi:[1,0] neg_lo:[1,0] neg_hi:[1,0]
	s_waitcnt lgkmcnt(3)
	v_lshlrev_b32_e32 v208, 16, v211
	v_and_b32_e32 v209, 0xffff0000, v211
	v_pk_mul_f32 v[84:85], v[84:85], v[174:175]
	v_pk_add_f32 v[174:175], v[206:207], 1.0 op_sel_hi:[1,0] neg_lo:[1,0] neg_hi:[1,0]
	s_waitcnt lgkmcnt(2)
	v_lshlrev_b32_e32 v210, 16, v212
	v_and_b32_e32 v211, 0xffff0000, v212
	v_pk_mul_f32 v[84:85], v[84:85], v[174:175]
	v_pk_add_f32 v[174:175], v[208:209], 1.0 op_sel_hi:[1,0] neg_lo:[1,0] neg_hi:[1,0]
	s_waitcnt lgkmcnt(1)
	v_lshlrev_b32_e32 v212, 16, v213
	v_and_b32_e32 v213, 0xffff0000, v213
	v_pk_mul_f32 v[84:85], v[84:85], v[174:175]
	v_pk_add_f32 v[174:175], v[210:211], 1.0 op_sel_hi:[1,0] neg_lo:[1,0] neg_hi:[1,0]
	s_waitcnt lgkmcnt(0)
	v_lshlrev_b32_e32 v216, 16, v197
	v_and_b32_e32 v217, 0xffff0000, v197
	v_pk_mul_f32 v[84:85], v[84:85], v[174:175]
	v_pk_add_f32 v[174:175], v[212:213], 1.0 op_sel_hi:[1,0] neg_lo:[1,0] neg_hi:[1,0]
	v_or_b32_e32 v197, s16, v133
	v_pk_mul_f32 v[84:85], v[84:85], v[174:175]
	v_pk_add_f32 v[174:175], v[216:217], 1.0 op_sel_hi:[1,0] neg_lo:[1,0] neg_hi:[1,0]
	s_cmp_lg_u32 s16, 0
	v_mov_b32_e32 v147, v146
	v_lshl_add_u32 v197, v197, 9, v134
	v_pk_mul_f32 v[84:85], v[84:85], v[174:175]
	s_cselect_b64 s[14:15], -1, 0
	ds_write_b64 v197, v[84:85]
	s_and_b64 s[30:31], s[40:41], s[14:15]
	v_mov_b64_e32 v[84:85], v[146:147]
	s_waitcnt lgkmcnt(0)
	s_barrier
	s_and_saveexec_b64 s[14:15], s[30:31]
	ds_read_b64 v[84:85], v134
	s_or_b64 exec, exec, s[14:15]
	s_cmp_eq_u32 s16, 0
	s_cselect_b64 s[14:15], -1, 0
	s_cmp_gt_u32 s16, 1
	v_cndmask_b32_e64 v147, 0, 1, s[14:15]
	s_cselect_b64 s[14:15], -1, 0
	v_cndmask_b32_e64 v174, 0, 1, s[14:15]
	v_cndmask_b32_e64 v147, v147, v174, s[40:41]
	v_and_b32_e32 v147, 1, v147
	v_cmp_eq_u32_e32 vcc, 1, v147
	s_and_saveexec_b64 s[14:15], vcc
	s_cbranch_execz .LBB0_451
	ds_read_b64 v[174:175], v167 offset:512
	s_waitcnt lgkmcnt(0)
	v_pk_mul_f32 v[84:85], v[84:85], v[174:175]

.LBB0_455:
	v_or_b32_e32 v31, s25, v101
	v_sub_u32_e32 v32, v99, v31
	v_sub_u32_e32 v33, 0, v32
	v_max_i32_e32 v32, v32, v33
	v_cvt_f32_u32_e32 v59, v32
	v_or_b32_e32 v32, 1, v31
	v_sub_u32_e32 v33, v99, v32
	v_sub_u32_e32 v34, 0, v33
	v_max_i32_e32 v33, v33, v34
	v_cvt_f32_u32_e32 v60, v33
	v_or_b32_e32 v33, 2, v31
	v_sub_u32_e32 v34, v99, v33
	v_sub_u32_e32 v35, 0, v34
	v_max_i32_e32 v34, v34, v35
	v_cvt_f32_u32_e32 v61, v34
	v_or_b32_e32 v34, 3, v31
	s_lshl_b32 s10, s8, 22
	v_sub_u32_e32 v35, v99, v34
	s_and_b32 s10, s10, 0x1c00000
	v_sub_u32_e32 v36, 0, v35
	s_add_u32 s10, s86, s10
	v_max_i32_e32 v35, v35, v36
	s_addc_u32 s11, s87, 0
	v_cvt_f32_u32_e32 v62, v35
	v_sub_u32_e32 v35, v107, v31
	s_add_u32 s12, s10, 0x4000000
	v_sub_u32_e32 v36, 0, v35
	s_addc_u32 s13, s11, 0
	s_ashr_i32 s14, s8, 3
	v_max_i32_e32 v35, v35, v36
	s_ashr_i32 s15, s14, 31
	v_cvt_f32_u32_e32 v63, v35
	v_sub_u32_e32 v35, v107, v32
	s_lshl_b64 s[14:15], s[14:15], 13
	v_sub_u32_e32 v36, 0, v35
	v_lshl_add_u64 v[2:3], s[14:15], 0, v[68:69]
	v_max_i32_e32 v35, v35, v36
	v_lshlrev_b64 v[2:3], 1, v[2:3]
	s_add_u32 s16, s10, 0x2000000
	v_cvt_f32_u32_e32 v64, v35
	v_sub_u32_e32 v35, v107, v33
	v_lshl_add_u64 v[4:5], s[12:13], 0, v[2:3]
	s_addc_u32 s17, s11, 0
	v_sub_u32_e32 v36, 0, v35
	v_lshl_add_u64 v[6:7], s[16:17], 0, v[2:3]
	global_load_dwordx4 v[14:17], v[4:5], off
	global_load_dwordx4 v[10:13], v[6:7], off
	v_lshl_add_u64 v[4:5], s[14:15], 0, v[66:67]
	v_max_i32_e32 v35, v35, v36
	v_lshlrev_b64 v[4:5], 1, v[4:5]
	v_lshlrev_b32_e32 v0, 1, v104
	v_add_u32_e32 v27, 1, v76
	v_cvt_f32_u32_e32 v65, v35
	v_sub_u32_e32 v35, v107, v34
	v_lshl_add_u64 v[6:7], s[12:13], 0, v[4:5]
	v_and_b32_e32 v0, 0x70, v0
	s_add_i32 s12, 0, 0x12000
	v_cvt_f32_i32_e32 v43, v27
	v_sub_u32_e32 v27, 0x80, v76
	s_movk_i32 s13, 0x90
	v_sub_u32_e32 v36, 0, v35
	v_add_u32_e32 v26, 0, v0
	v_add_u32_e32 v0, s12, v0
	v_cvt_f32_i32_e32 v52, v27
	v_mul_lo_u32 v27, v76, s13
	v_max_i32_e32 v35, v35, v36
	v_add_u32_e32 v53, v26, v27
	v_add_u32_e32 v54, v0, v27
	v_ashrrev_i32_e32 v27, 3, v74
	v_cvt_f32_u32_e32 v74, v35
	v_sub_u32_e32 v35, v105, v31
	v_sub_u32_e32 v36, 0, v35
	v_max_i32_e32 v35, v35, v36
	v_cvt_f32_u32_e32 v76, v35
	v_sub_u32_e32 v35, v105, v32
	v_lshl_add_u64 v[2:3], s[10:11], 0, v[2:3]
	v_sub_u32_e32 v36, 0, v35
	global_load_dwordx4 v[18:21], v[2:3], off
	global_load_dwordx4 v[22:25], v[6:7], off
	v_lshl_add_u64 v[2:3], s[16:17], 0, v[4:5]
	v_lshl_add_u64 v[4:5], s[10:11], 0, v[4:5]
	v_add_u32_e32 v28, 1, v27
	v_max_i32_e32 v35, v35, v36
	global_load_dwordx4 v[6:9], v[2:3], off
	s_nop 0
	global_load_dwordx4 v[2:5], v[4:5], off
	v_cvt_f32_i32_e32 v55, v28
	v_sub_u32_e32 v28, 0x80, v27
	v_mul_lo_u32 v27, v27, s13
	v_cvt_f32_u32_e32 v77, v35
	v_sub_u32_e32 v35, v105, v33
	v_add_u32_e32 v58, v0, v27
	v_lshlrev_b32_e32 v0, 1, v100
	v_sub_u32_e32 v36, 0, v35
	v_add_u32_e32 v42, 0, v0
	v_max_i32_e32 v35, v35, v36
	v_mad_u64_u32 v[44:45], s[10:11], v78, s13, v[42:43]
	v_cvt_f32_u32_e32 v78, v35
	v_sub_u32_e32 v35, v105, v34
	v_sub_u32_e32 v36, 0, v35
	v_max_i32_e32 v35, v35, v36
	v_cvt_f32_u32_e32 v79, v35
	v_sub_u32_e32 v35, v103, v31
	v_sub_u32_e32 v36, 0, v35
	v_max_i32_e32 v35, v35, v36
	v_cvt_f32_u32_e32 v80, v35
	v_sub_u32_e32 v35, v103, v32
	v_sub_u32_e32 v36, 0, v35
	v_max_i32_e32 v35, v35, v36
	v_cvt_f32_u32_e32 v81, v35
	v_sub_u32_e32 v35, v103, v33
	v_sub_u32_e32 v36, 0, v35
	v_max_i32_e32 v35, v35, v36
	v_cvt_f32_u32_e32 v82, v35
	v_sub_u32_e32 v35, v103, v34
	v_sub_u32_e32 v36, 0, v35
	v_add_u32_e32 v57, v26, v27
	v_or_b32_e32 v26, 64, v99
	v_max_i32_e32 v35, v35, v36
	v_cvt_f32_u32_e32 v83, v35
	v_sub_u32_e32 v35, v26, v31
	v_sub_u32_e32 v36, 0, v35
	v_max_i32_e32 v35, v35, v36
	v_cvt_f32_u32_e32 v84, v35
	v_sub_u32_e32 v35, v26, v32
	v_sub_u32_e32 v36, 0, v35
	v_max_i32_e32 v35, v35, v36
	v_cvt_f32_u32_e32 v85, v35
	v_sub_u32_e32 v35, v26, v33
	v_sub_u32_e32 v36, 0, v35
	v_max_i32_e32 v35, v35, v36
	v_sub_u32_e32 v26, v26, v34
	v_cvt_f32_u32_e32 v86, v35
	v_sub_u32_e32 v35, 0, v26
	v_or_b32_e32 v27, 0x50, v99
	v_max_i32_e32 v26, v26, v35
	v_cvt_f32_u32_e32 v87, v26
	v_sub_u32_e32 v26, v27, v31
	v_sub_u32_e32 v35, 0, v26
	v_max_i32_e32 v26, v26, v35
	v_cvt_f32_u32_e32 v88, v26
	v_sub_u32_e32 v26, v27, v32
	v_sub_u32_e32 v35, 0, v26
	v_max_i32_e32 v26, v26, v35
	v_cvt_f32_u32_e32 v89, v26
	v_sub_u32_e32 v26, v27, v33
	v_sub_u32_e32 v35, 0, v26
	v_max_i32_e32 v26, v26, v35
	v_cvt_f32_u32_e32 v90, v26
	v_sub_u32_e32 v26, v27, v34
	v_sub_u32_e32 v27, 0, v26
	v_cvt_f32_i32_e32 v56, v28
	v_or_b32_e32 v28, 0x60, v99
	v_max_i32_e32 v26, v26, v27
	v_cvt_f32_u32_e32 v91, v26
	v_sub_u32_e32 v26, v28, v31
	v_sub_u32_e32 v27, 0, v26
	v_max_i32_e32 v26, v26, v27
	v_cvt_f32_u32_e32 v92, v26
	v_sub_u32_e32 v26, v28, v32
	v_sub_u32_e32 v27, 0, v26
	v_max_i32_e32 v26, v26, v27
	v_cvt_f32_u32_e32 v93, v26
	v_sub_u32_e32 v26, v28, v33
	v_sub_u32_e32 v27, 0, v26
	v_max_i32_e32 v26, v26, v27
	v_cvt_f32_u32_e32 v94, v26
	v_sub_u32_e32 v26, v28, v34
	v_sub_u32_e32 v27, 0, v26
	v_or_b32_e32 v29, 0x70, v102
	v_max_i32_e32 v26, v26, v27
	v_cvt_f32_u32_e32 v95, v26
	v_sub_u32_e32 v26, v29, v31
	v_sub_u32_e32 v27, 0, v26
	v_max_i32_e32 v26, v26, v27
	v_cvt_f32_u32_e32 v102, v26
	v_sub_u32_e32 v26, v29, v32
	v_sub_u32_e32 v27, 0, v26
	v_max_i32_e32 v26, v26, v27
	v_cvt_f32_u32_e32 v103, v26
	v_sub_u32_e32 v26, v29, v33
	v_sub_u32_e32 v27, 0, v26
	v_max_i32_e32 v26, v26, v27
	v_cvt_f32_u32_e32 v104, v26
	v_sub_u32_e32 v26, v29, v34
	v_sub_u32_e32 v27, 0, v26
	v_max_i32_e32 v26, v26, v27
	s_andn2_b32 s25, s25, 63
	v_cvt_f32_u32_e32 v105, v26
	v_or_b32_e32 v26, s25, v99
	v_readlane_b32 s11, v255, 22
	v_mul_lo_u32 v32, v26, s18
	v_or_b32_e32 v37, 64, v100
	v_add_u32_e32 v34, s11, v0
	v_add_u32_e32 v0, s11, v32
	v_mul_u32_u24_e32 v30, 0x90, v29
	v_mul_u32_u24_e32 v27, 0x110, v29
	v_add_u32_e32 v28, 0x1100, v0
	v_add_u32_e32 v29, 0x2200, v0
	v_add_u32_e32 v36, 0x3300, v0
	v_or_b32_e32 v38, v37, v108
	v_lshlrev_b32_e32 v37, 1, v37
	v_mul_u32_u24_e32 v33, 0x90, v114
	v_add_u32_e32 v112, v0, v37
	v_add_u32_e32 v113, v28, v37
	v_add_u32_e32 v114, v29, v37
	v_add_u32_e32 v115, v36, v37
	v_or_b32_e32 v37, 0x60, v100
	s_add_i32 s10, s11, s27
	s_add_i32 s12, s12, s26
	v_or_b32_e32 v39, v37, v108
	v_lshlrev_b32_e32 v37, 1, v37
	v_add_u32_e32 v45, s10, v100
	v_lshl_add_u32 v31, v116, 1, s12
	v_add_u32_e32 v107, v0, v125
	v_add_u32_e32 v111, v36, v125
	v_add_u32_e32 v100, v0, v37
	v_add_u32_e32 v118, v36, v37
	v_mul_lo_u32 v36, v26, s13
	v_and_b32_e32 v26, 48, v117
	v_or_b32_e32 v0, s25, v101
	v_readlane_b32 s12, v255, 27
	v_mul_lo_u32 v40, v0, s18
	v_lshlrev_b32_e32 v0, 2, v26
	v_readlane_b32 s13, v255, 28
	s_lshl_b32 s10, s24, 6
	v_ashrrev_i32_e32 v46, 2, v70
	v_lshl_add_u64 v[48:49], s[12:13], 0, v[0:1]
	v_readlane_b32 s12, v254, 0
	v_readlane_b32 s13, v254, 1
	s_add_i32 s10, s10, 0
	s_load_dword s73, s[12:13], 0x98
	v_add_u32_e32 v109, v28, v125
	v_add_u32_e32 v108, v28, v37
	v_add_u32_e32 v116, v29, v37
	v_lshl_add_u32 v37, v99, 2, s10
	v_mul_lo_u32 v28, v46, s18
	s_lshl_b64 s[10:11], s[8:9], 14
	v_add_u32_e32 v110, v29, v125
	v_add3_u32 v70, 0, v28, v0
	v_mov_b32_e32 v29, s11
	v_or_b32_e32 v0, s10, v72
	v_lshlrev_b32_e32 v28, 7, v99
	s_lshl_b32 s9, s24, 11
	v_readlane_b32 s10, v255, 12
	v_mul_u32_u24_e32 v35, 0x90, v132
	v_mul_u32_u24_e32 v38, 0x90, v38
	v_mul_u32_u24_e32 v39, 0x90, v39
	v_or3_b32 v28, s9, v28, v0
	v_readlane_b32 s11, v255, 13
	v_readlane_b32 s70, v255, 32
	v_readlane_b32 s66, v255, 34
	v_readlane_b32 s60, v255, 36
	v_readlane_b32 s62, v255, 38
	v_readlane_b32 s64, v255, 40
	v_readlane_b32 s34, v255, 42
	v_readlane_b32 s52, v255, 44
	v_readlane_b32 s54, v255, 46
	v_readlane_b32 s58, v255, 48
	v_ashrrev_i32_e32 v47, 31, v46
	v_lshl_add_u64 v[50:51], s[10:11], 0, v[28:29]
	s_lshl_b64 s[10:11], s[2:3], 14
	v_add_u32_e32 v72, v42, v30
	v_add_u32_e32 v99, v45, v27
	v_add_u32_e32 v101, v31, v33
	v_add_u32_e32 v117, v34, v32
	v_add_u32_e32 v119, v31, v35
	v_add_u32_e32 v120, v31, v38
	v_add_u32_e32 v121, v31, v39
	v_add_u32_e32 v106, v106, v36
	v_lshlrev_b32_e32 v0, 1, v26
	v_add_u32_e32 v122, v37, v40
	v_readlane_b32 s69, v255, 31
	v_readlane_b32 s71, v255, 33
	v_readlane_b32 s67, v255, 35
	v_readlane_b32 s61, v255, 37
	v_readlane_b32 s63, v255, 39
	v_readlane_b32 s65, v255, 41
	v_readlane_b32 s35, v255, 43
	v_readlane_b32 s53, v255, 45
	v_readlane_b32 s55, v255, 47
	v_readlane_b32 s59, v255, 49
	v_readlane_b32 s14, v255, 29
	v_readlane_b32 s15, v255, 30
	s_waitcnt vmcnt(0)
	s_branch .LBB0_457

.LBB0_457:
	s_add_i32 s3, s8, s2
	s_cmpk_gt_i32 s3, 0x7ff
	s_cselect_b64 s[12:13], -1, 0
	s_cmpk_lt_i32 s3, 0x800
	s_cselect_b32 s14, s3, -1
	s_and_b32 s9, s8, 7
	s_cmp_eq_u32 s9, 1
	s_cselect_b64 vcc, -1, 0
	s_cmp_lg_u32 s9, 2
	v_cndmask_b32_e32 v26, v181, v182, vcc
	s_cselect_b64 vcc, -1, 0
	s_cmp_lg_u32 s9, 3
	v_cndmask_b32_e32 v26, v183, v26, vcc
	s_cselect_b64 vcc, -1, 0
	s_cmp_lg_u32 s9, 4
	v_cndmask_b32_e32 v26, v184, v26, vcc
	s_cselect_b64 vcc, -1, 0
	s_cmp_lg_u32 s9, 5
	v_cndmask_b32_e32 v26, v185, v26, vcc
	s_cselect_b64 vcc, -1, 0
	s_cmp_lg_u32 s9, 6
	v_cndmask_b32_e32 v26, v186, v26, vcc
	s_cselect_b64 vcc, -1, 0
	s_cmp_lg_u32 s9, 7
	v_cndmask_b32_e32 v26, v187, v26, vcc
	s_cselect_b64 vcc, -1, 0
	v_cndmask_b32_e32 v123, v188, v26, vcc
	v_mul_f32_e32 v26, v123, v43
	v_exp_f32_e32 v26, v26
	v_mul_f32_e32 v27, v123, v52
	v_exp_f32_e32 v38, v27
	s_waitcnt vmcnt(2)
	v_lshlrev_b32_e32 v30, 16, v2
	v_and_b32_e32 v31, 0xffff0000, v2
	v_lshlrev_b32_e32 v32, 16, v3
	v_and_b32_e32 v33, 0xffff0000, v3
	v_lshlrev_b32_e32 v34, 16, v4
	v_and_b32_e32 v35, 0xffff0000, v4
	v_lshlrev_b32_e32 v36, 16, v5
	v_and_b32_e32 v37, 0xffff0000, v5
	v_pk_mul_f32 v[28:29], v[26:27], v[32:33] op_sel_hi:[0,1]
	v_pk_mul_f32 v[40:41], v[26:27], v[30:31] op_sel_hi:[0,1]
	v_pk_mul_f32 v[124:125], v[26:27], v[36:37] op_sel_hi:[0,1]
	v_pk_mul_f32 v[126:127], v[26:27], v[34:35] op_sel_hi:[0,1]
	v_cvt_pk_bf16_f32 v26, v40, v41
	v_cvt_pk_bf16_f32 v27, v28, v29
	v_cvt_pk_bf16_f32 v28, v126, v127
	v_cvt_pk_bf16_f32 v29, v124, v125
	ds_write_b128 v53, v[26:29] offset:18432
	v_pk_mul_f32 v[28:29], v[38:39], v[32:33] op_sel_hi:[0,1]
	v_pk_mul_f32 v[26:27], v[38:39], v[30:31] op_sel_hi:[0,1]
	v_pk_mul_f32 v[30:31], v[38:39], v[36:37] op_sel_hi:[0,1]
	v_pk_mul_f32 v[32:33], v[38:39], v[34:35] op_sel_hi:[0,1]
	v_cvt_pk_bf16_f32 v26, v26, v27
	v_cvt_pk_bf16_f32 v27, v28, v29
	v_cvt_pk_bf16_f32 v28, v32, v33
	v_cvt_pk_bf16_f32 v29, v30, v31
	ds_write_b128 v53, v[2:5]
	ds_write_b128 v53, v[26:29] offset:36864
	ds_write_b128 v53, v[6:9] offset:55296
	ds_write_b128 v54, v[22:25]
	v_mul_f32_e32 v26, v123, v55
	v_exp_f32_e32 v26, v26
	v_mul_f32_e32 v27, v123, v56
	v_exp_f32_e32 v38, v27
	v_lshlrev_b32_e32 v30, 16, v18
	v_and_b32_e32 v31, 0xffff0000, v18
	v_lshlrev_b32_e32 v32, 16, v19
	v_and_b32_e32 v33, 0xffff0000, v19
	v_lshlrev_b32_e32 v34, 16, v20
	v_and_b32_e32 v35, 0xffff0000, v20
	v_lshlrev_b32_e32 v36, 16, v21
	v_and_b32_e32 v37, 0xffff0000, v21
	v_pk_mul_f32 v[28:29], v[26:27], v[32:33] op_sel_hi:[0,1]
	v_pk_mul_f32 v[40:41], v[26:27], v[30:31] op_sel_hi:[0,1]
	v_pk_mul_f32 v[124:125], v[26:27], v[36:37] op_sel_hi:[0,1]
	v_pk_mul_f32 v[126:127], v[26:27], v[34:35] op_sel_hi:[0,1]
	v_cvt_pk_bf16_f32 v26, v40, v41
	v_cvt_pk_bf16_f32 v27, v28, v29
	v_cvt_pk_bf16_f32 v28, v126, v127
	v_cvt_pk_bf16_f32 v29, v124, v125
	ds_write_b128 v57, v[26:29] offset:18432
	v_pk_mul_f32 v[28:29], v[38:39], v[32:33] op_sel_hi:[0,1]
	v_pk_mul_f32 v[26:27], v[38:39], v[30:31] op_sel_hi:[0,1]
	v_pk_mul_f32 v[30:31], v[38:39], v[36:37] op_sel_hi:[0,1]
	v_pk_mul_f32 v[32:33], v[38:39], v[34:35] op_sel_hi:[0,1]
	v_cvt_pk_bf16_f32 v26, v26, v27
	v_cvt_pk_bf16_f32 v27, v28, v29
	v_cvt_pk_bf16_f32 v28, v32, v33
	v_cvt_pk_bf16_f32 v29, v30, v31
	s_cmp_lt_i32 s14, 0
	ds_write_b128 v57, v[18:21]
	ds_write_b128 v57, v[26:29] offset:36864
	ds_write_b128 v57, v[10:13] offset:55296
	ds_write_b128 v58, v[14:17]
	s_waitcnt lgkmcnt(0)
	s_barrier
	s_cbranch_scc1 .LBB0_456
	s_lshr_b32 s80, s14, 3
	s_lshl_b32 s14, s14, 22
	s_lshl_b64 s[16:17], s[80:81], 13
	s_and_b32 s14, s14, 0x1c00000
	s_add_u32 s14, s86, s14
	s_addc_u32 s15, s87, 0
	s_add_u32 s24, s14, 0x2000000
	s_addc_u32 s25, s15, 0
	s_add_u32 s26, s14, 0x4000000
	v_lshl_add_u64 v[2:3], s[16:17], 0, v[66:67]
	v_lshl_add_u64 v[12:13], s[16:17], 0, v[68:69]
	s_addc_u32 s27, s15, 0
	v_lshlrev_b64 v[10:11], 1, v[2:3]
	v_lshlrev_b64 v[12:13], 1, v[12:13]
	v_lshl_add_u64 v[2:3], s[14:15], 0, v[10:11]
	v_lshl_add_u64 v[6:7], s[24:25], 0, v[10:11]
	v_lshl_add_u64 v[10:11], s[26:27], 0, v[10:11]
	v_lshl_add_u64 v[14:15], s[14:15], 0, v[12:13]
	global_load_dwordx4 v[2:5], v[2:3], off
	s_nop 0
	global_load_dwordx4 v[6:9], v[6:7], off
	s_nop 0
	global_load_dwordx4 v[22:25], v[10:11], off
	global_load_dwordx4 v[18:21], v[14:15], off
	v_lshl_add_u64 v[10:11], s[24:25], 0, v[12:13]
	v_lshl_add_u64 v[14:15], s[26:27], 0, v[12:13]
	global_load_dwordx4 v[10:13], v[10:11], off
	s_nop 0
	global_load_dwordx4 v[14:17], v[14:15], off
	s_branch .LBB0_456
